# LRU pass-1 conv: v_pk_mul + two v_add (+ pair-building v_mov) rewritten as v_fma chains (56 sites, -138 VALU per wave-unit)
# speedup vs baseline: 1.0113x; 1.0071x over previous
; #define LAS __attribute__((address_space(3)))
; template <int PASS>
; __device__ __forceinline__ void lru_unit(const LruPtrs& args, LAS unsigned char* lds, int chunk, int bl, int g, int ck) {
;     ...
;             for (int i = 0; i < 5; ++i) { const int idx = lane + 64 * i, r = idx >> 3, ch = idx & 7;
;                 if (r < 35) { *(LAS v2u*)(XT + r * 68 + ch * 8) = (v2u){xv[i].x, xv[i].y}; *(LAS v2u*)(XT + r * 68 + ch * 8 + 4) = (v2u){xv[i].z, xv[i].w}; } }
;         }
;         __syncthreads();
;         v2u xw[4][8];
; #pragma unroll
;         for (int k = 0; k < 4; ++k)
; #pragma unroll
;             for (int q = 0; q < 8; ++q) xw[k][q] = *(const LAS v2u*)(XT + (n + k) * 68 + 8 * q + 4 * hi);
;         float xc[8][4];
; #pragma unroll
;         for (int q = 0; q < 8; ++q) { const f32x4 bb = *(const LAS f32x4*)(PRM + 4 * 64 + 8 * q + 4 * hi);
; #pragma unroll
;             for (int p = 0; p < 4; ++p) xc[q][p] = bb[p]; }
; #pragma unroll
;         for (int k = 0; k < 4; ++k) {
; #pragma unroll
;             for (int q = 0; q < 8; ++q) { const f32x4 cw = *(const LAS f32x4*)(PRM + k * 64 + 8 * q + 4 * hi);
;                 xc[q][0] += cw[0] * pg8::bf_lo(xw[k][q].x); xc[q][1] += cw[1] * pg8::bf_hi(xw[k][q].x); xc[q][2] += cw[2] * pg8::bf_lo(xw[k][q].y); xc[q][3] += cw[3] * pg8::bf_hi(xw[k][q].y); }
.LBB0_443:
	s_or_b64 exec, exec, s[4:5]
	s_mul_i32 s4, s48, 0x1300
	s_add_i32 s50, s4, 0
	v_lshl_add_u32 v0, v26, 1, s50
	s_movk_i32 s4, 0x88
	v_mad_u32_u24 v22, v25, s4, v0
	v_add_u32_e32 v23, 0x8000, v22
	s_waitcnt vmcnt(0)
	ds_write_b32 v179, v178 offset:12288
	ds_write2_b64 v23, v[6:7], v[8:9] offset1:1
	v_add_u32_e32 v6, 0x8440, v22
	ds_write2_b64 v6, v[2:3], v[4:5] offset1:1
	v_add_u32_e32 v2, 0x8880, v22
	ds_write2_b64 v2, v[14:15], v[16:17] offset1:1
	v_add_u32_e32 v2, 0x8cc0, v22
	ds_write2_b64 v2, v[10:11], v[12:13] offset1:1
	s_and_saveexec_b64 s[4:5], vcc
	v_mul_u32_u24_e32 v2, 0x88, v27
	v_add3_u32 v0, v0, v2, s79
	ds_write2_b64 v0, v[18:19], v[20:21] offset1:1
	s_or_b64 exec, exec, s[4:5]
	v_lshrrev_b32_e32 v2, 3, v24
	v_and_b32_e32 v87, 31, v24
	v_and_b32_e32 v88, 4, v2
	v_lshlrev_b32_e32 v2, 1, v88
	v_mul_u32_u24_e32 v3, 0x88, v87
	v_add3_u32 v2, s50, v2, v3
	v_add_u32_e32 v10, 0x8000, v2
	v_lshl_add_u32 v89, v88, 2, 0
	s_waitcnt lgkmcnt(0)
	s_barrier
	ds_read2_b64 v[90:93], v10 offset1:2
	ds_read2_b64 v[82:85], v10 offset0:4 offset1:6
	ds_read2_b64 v[50:53], v10 offset0:8 offset1:10
	ds_read2_b64 v[2:5], v10 offset0:12 offset1:14
	ds_read2_b64 v[94:97], v10 offset0:17 offset1:19
	ds_read2_b64 v[98:101], v10 offset0:21 offset1:23
	ds_read2_b64 v[54:57], v10 offset0:25 offset1:27
	ds_read2_b64 v[6:9], v10 offset0:29 offset1:31
	ds_read2_b64 v[34:37], v10 offset0:34 offset1:36
	ds_read2_b64 v[26:29], v10 offset0:38 offset1:40
	ds_read2_b64 v[18:21], v10 offset0:42 offset1:44
	ds_read2_b64 v[66:69], v10 offset0:46 offset1:48
	ds_read2_b64 v[38:41], v10 offset0:51 offset1:53
	ds_read2_b64 v[30:33], v10 offset0:55 offset1:57
	ds_read2_b64 v[22:25], v10 offset0:59 offset1:61
	ds_read2_b64 v[70:73], v10 offset0:63 offset1:65
	ds_read_b128 v[102:105], v89 offset:13312
	ds_read_b128 v[106:109], v89 offset:13344
	ds_read_b128 v[110:113], v89 offset:13376
	ds_read_b128 v[114:117], v89 offset:13408
	ds_read_b128 v[74:77], v89 offset:13440
	ds_read_b128 v[58:61], v89 offset:13472
	ds_read_b128 v[42:45], v89 offset:13504
	ds_read_b128 v[10:13], v89 offset:13536
	ds_read_b128 v[118:121], v89 offset:12288
	ds_read_b128 v[122:125], v89 offset:12320
	ds_read_b128 v[126:129], v89 offset:12352
	ds_read_b128 v[130:133], v89 offset:12384
	ds_read_b128 v[78:81], v89 offset:12416
	ds_read_b128 v[62:65], v89 offset:12448
	ds_read_b128 v[46:49], v89 offset:12480
	ds_read_b128 v[14:17], v89 offset:12512
	ds_read_b128 v[134:137], v89 offset:12544
	s_waitcnt lgkmcnt(14)
	v_lshlrev_b32_e32 v143, 16, v94
	v_lshlrev_b32_e32 v142, 16, v90
	s_waitcnt lgkmcnt(8)
	ds_read_b128 v[138:141], v89 offset:12576
	s_waitcnt lgkmcnt(1)
	v_fma_f32 v102, v118, v142, v102
	v_fma_f32 v144, v134, v143, v102
	v_and_b32_e32 v143, 0xffff0000, v94
	v_and_b32_e32 v142, 0xffff0000, v90
	v_fma_f32 v90, v119, v142, v103
	v_fma_f32 v134, v135, v143, v90
	v_lshlrev_b32_e32 v102, 16, v91
	v_lshlrev_b32_e32 v103, 16, v95
	v_fma_f32 v90, v120, v102, v104
	v_fma_f32 v135, v136, v103, v90
	v_and_b32_e32 v95, 0xffff0000, v95
	v_and_b32_e32 v94, 0xffff0000, v91
	v_fma_f32 v90, v121, v94, v105
	v_fma_f32 v136, v137, v95, v90
	v_lshlrev_b32_e32 v91, 16, v96
	v_lshlrev_b32_e32 v90, 16, v92
	s_waitcnt lgkmcnt(0)
	v_fma_f32 v90, v122, v90, v106
	v_fma_f32 v122, v138, v91, v90
	v_and_b32_e32 v91, 0xffff0000, v96
	v_and_b32_e32 v90, 0xffff0000, v92
	v_fma_f32 v90, v123, v90, v107
	v_fma_f32 v123, v139, v91, v90
	v_mov_b32_e32 v94, v124
	v_lshlrev_b32_e32 v91, 16, v97
	v_lshlrev_b32_e32 v90, 16, v93
	v_mov_b32_e32 v95, v140
	v_pk_mul_f32 v[90:91], v[94:95], v[90:91]
	v_add_f32_e32 v90, v108, v90
	v_add_f32_e32 v108, v90, v91
	v_and_b32_e32 v91, 0xffff0000, v97
	v_and_b32_e32 v90, 0xffff0000, v93
	v_fma_f32 v90, v125, v90, v109
	v_fma_f32 v124, v141, v91, v90
	v_lshlrev_b32_e32 v103, 16, v98
	ds_read_b128 v[90:93], v89 offset:12608
	ds_read_b128 v[94:97], v89 offset:12640
	v_lshlrev_b32_e32 v102, 16, v82
	s_and_b32 s4, s49, 0x1ffffe00
	s_waitcnt lgkmcnt(1)
	v_mov_b32_e32 v105, v90
	v_fma_f32 v90, v126, v102, v110
	v_fma_f32 v125, v105, v103, v90
	s_lshl_b32 s5, s2, 5
	v_and_b32_e32 v103, 0xffff0000, v98
	v_and_b32_e32 v102, 0xffff0000, v82
	v_mov_b32_e32 v90, v127
	v_fma_f32 v82, v90, v102, v111
	v_fma_f32 v126, v91, v103, v82
	v_lshlrev_b32_e32 v91, 16, v99
	v_lshlrev_b32_e32 v90, 16, v83
	v_fma_f32 v82, v128, v90, v112
	v_fma_f32 v127, v92, v91, v82
	v_and_b32_e32 v91, 0xffff0000, v99
	v_and_b32_e32 v90, 0xffff0000, v83
	v_fma_f32 v82, v129, v90, v113
	v_fma_f32 v128, v93, v91, v82
	v_lshlrev_b32_e32 v83, 16, v100
	v_lshlrev_b32_e32 v82, 16, v84
	s_waitcnt lgkmcnt(0)
	v_fma_f32 v82, v130, v82, v114
	v_fma_f32 v129, v94, v83, v82
	v_and_b32_e32 v83, 0xffff0000, v100
	v_and_b32_e32 v82, 0xffff0000, v84
	v_fma_f32 v82, v131, v82, v115
	v_fma_f32 v130, v95, v83, v82
	v_lshlrev_b32_e32 v83, 16, v101
	v_lshlrev_b32_e32 v82, 16, v85
	v_fma_f32 v82, v132, v82, v116
	v_fma_f32 v131, v96, v83, v82
	v_mov_b32_e32 v96, v133
	v_and_b32_e32 v83, 0xffff0000, v101
	v_and_b32_e32 v82, 0xffff0000, v85
	v_pk_mul_f32 v[82:83], v[96:97], v[82:83]
	v_lshlrev_b32_e32 v91, 16, v54
	v_add_f32_e32 v82, v117, v82
	v_add_f32_e32 v117, v82, v83
	ds_read_b128 v[82:85], v89 offset:12672
	ds_read_b128 v[94:97], v89 offset:12704
	v_lshlrev_b32_e32 v90, 16, v50
	s_or_b32 s4, s5, s4
	s_waitcnt lgkmcnt(1)
	v_fma_f32 v74, v78, v90, v74
	v_fma_f32 v132, v82, v91, v74
	v_and_b32_e32 v91, 0xffff0000, v54
	v_and_b32_e32 v90, 0xffff0000, v50
	v_fma_f32 v50, v79, v90, v75
	v_fma_f32 v133, v83, v91, v50
	v_lshlrev_b32_e32 v74, 16, v51
	v_lshlrev_b32_e32 v75, 16, v55
	v_fma_f32 v50, v80, v74, v76
	v_fma_f32 v92, v84, v75, v50
	v_and_b32_e32 v55, 0xffff0000, v55
	v_and_b32_e32 v54, 0xffff0000, v51
	v_fma_f32 v50, v81, v54, v77
	v_fma_f32 v54, v85, v55, v50
	v_lshlrev_b32_e32 v51, 16, v56
	v_lshlrev_b32_e32 v50, 16, v52
	s_waitcnt lgkmcnt(0)
; __device__ __forceinline__ unsigned cvt_pk_bf16(float lo, float hi) { unsigned r; asm volatile("v_cvt_pk_bf16_f32 %0, %1, %2" : "=v"(r) : "v"(lo), "v"(hi)); return r; }
; #define GAS __attribute__((address_space(1)))
; #define LAS __attribute__((address_space(3)))
; template <int PASS>
; __device__ __forceinline__ void lru_unit(const LruPtrs& args, LAS unsigned char* lds, int chunk, int bl, int g, int ck) {
;     ...
;         for (int k = 0; k < 4; ++k) {
; #pragma unroll
;             for (int q = 0; q < 8; ++q) { const f32x4 cw = *(const LAS f32x4*)(PRM + k * 64 + 8 * q + 4 * hi);
;                 xc[q][0] += cw[0] * pg8::bf_lo(xw[k][q].x); xc[q][1] += cw[1] * pg8::bf_hi(xw[k][q].x); xc[q][2] += cw[2] * pg8::bf_lo(xw[k][q].y); xc[q][3] += cw[3] * pg8::bf_hi(xw[k][q].y); }
;         }
;         f32x16 ar[2], ai_[2];
; #pragma unroll
;         for (int rb = 0; rb < 2; ++rb) { ar[rb] = f32x16{}; ai_[rb] = f32x16{}; }
;         const GAS bf16* wrf = (const GAS bf16*)(ws + WS_WRF) + (size_t)g * (2 * 2 * 4 * 64 * 8) + lane * 8;
; #pragma unroll
;         for (int ks = 0; ks < 4; ++ks) {
;             v4u bw; bw.x = pg8::cvt_pk_bf16(xc[2 * ks][0], xc[2 * ks][1]); bw.y = pg8::cvt_pk_bf16(xc[2 * ks][2], xc[2 * ks][3]); bw.z = pg8::cvt_pk_bf16(xc[2 * ks + 1][0], xc[2 * ks + 1][1]); bw.w = pg8::cvt_pk_bf16(xc[2 * ks + 1][2], xc[2 * ks + 1][3]);
;             const bf16x8 bfr = __builtin_bit_cast(bf16x8, bw);
; #pragma unroll
;             for (int rb = 0; rb < 2; ++rb) {
;                 const bf16x8 wr_ = __builtin_bit_cast(bf16x8, *(const GAS v4u*)(wrf + ((0 * 2 + rb) * 4 + ks) * 512));
;                 const bf16x8 wi_ = __builtin_bit_cast(bf16x8, *(const GAS v4u*)(wrf + ((1 * 2 + rb) * 4 + ks) * 512));
;                 ar[rb] = __builtin_amdgcn_mfma_f32_32x32x16_bf16(wr_, bfr, ar[rb], 0, 0, 0);
	v_fma_f32 v50, v62, v50, v58
	v_fma_f32 v51, v94, v51, v50
	v_and_b32_e32 v75, 0xffff0000, v56
	v_and_b32_e32 v74, 0xffff0000, v52
	v_fma_f32 v50, v63, v74, v59
	v_fma_f32 v52, v95, v75, v50
	v_lshlrev_b32_e32 v59, 16, v57
	v_lshlrev_b32_e32 v58, 16, v53
	v_mov_b32_e32 v63, v96
	v_and_b32_e32 v57, 0xffff0000, v57
	v_and_b32_e32 v56, 0xffff0000, v53
	v_fma_f32 v50, v64, v58, v60
	v_fma_f32 v50, v63, v59, v50
	v_fma_f32 v53, v65, v56, v61
	v_fma_f32 v53, v97, v57, v53
	ds_read_b128 v[56:59], v89 offset:12736
	ds_read_b128 v[74:77], v89 offset:12768
	v_lshlrev_b32_e32 v61, 16, v6
	v_lshlrev_b32_e32 v60, 16, v2
	s_waitcnt lgkmcnt(1)
	v_fma_f32 v42, v46, v60, v42
	v_fma_f32 v94, v56, v61, v42
	v_and_b32_e32 v61, 0xffff0000, v6
	v_and_b32_e32 v60, 0xffff0000, v2
	v_fma_f32 v2, v47, v60, v43
	v_fma_f32 v93, v57, v61, v2
	v_lshlrev_b32_e32 v42, 16, v3
	v_lshlrev_b32_e32 v43, 16, v7
	v_fma_f32 v2, v48, v42, v44
	v_fma_f32 v116, v58, v43, v2
	v_and_b32_e32 v7, 0xffff0000, v7
	v_and_b32_e32 v6, 0xffff0000, v3
	v_mov_b32_e32 v58, v49
	v_pk_mul_f32 v[2:3], v[58:59], v[6:7]
	v_lshlrev_b32_e32 v7, 16, v38
	v_add_f32_e32 v2, v45, v2
	ds_read_b128 v[56:59], v89 offset:12800
	ds_read_b128 v[60:63], v89 offset:12832
	ds_read_b128 v[96:99], v89 offset:12864
	ds_read_b128 v[118:121], v89 offset:12896
	ds_read_b128 v[46:49], v89 offset:12928
	ds_read_b128 v[42:45], v89 offset:12960
	ds_read_b128 v[82:85], v89 offset:12992
	ds_read_b128 v[78:81], v89 offset:13024
	ds_read_b128 v[100:103], v89 offset:13056
	v_lshlrev_b32_e32 v6, 16, v34
	s_waitcnt lgkmcnt(8)
	v_mov_b32_e32 v64, v56
	ds_read_b128 v[104:107], v89 offset:13088
	s_waitcnt lgkmcnt(1)
	v_fma_f32 v6, v64, v6, v144
	v_fma_f32 v115, v100, v7, v6
	v_and_b32_e32 v7, 0xffff0000, v38
	v_and_b32_e32 v6, 0xffff0000, v34
	v_fma_f32 v6, v57, v6, v134
	v_fma_f32 v114, v101, v7, v6
	v_lshlrev_b32_e32 v7, 16, v39
	v_lshlrev_b32_e32 v6, 16, v35
	v_fma_f32 v6, v58, v6, v135
	v_fma_f32 v113, v102, v7, v6
	v_and_b32_e32 v7, 0xffff0000, v39
	v_and_b32_e32 v6, 0xffff0000, v35
	v_fma_f32 v6, v59, v6, v136
	v_fma_f32 v112, v103, v7, v6
	v_lshlrev_b32_e32 v7, 16, v40
	v_lshlrev_b32_e32 v6, 16, v36
	s_waitcnt lgkmcnt(0)
	v_fma_f32 v6, v60, v6, v122
	v_fma_f32 v111, v104, v7, v6
	v_and_b32_e32 v7, 0xffff0000, v40
	v_and_b32_e32 v6, 0xffff0000, v36
	v_fma_f32 v6, v61, v6, v123
	v_fma_f32 v110, v105, v7, v6
	v_lshlrev_b32_e32 v7, 16, v41
	v_lshlrev_b32_e32 v6, 16, v37
	v_fma_f32 v6, v62, v6, v108
	v_fma_f32 v109, v106, v7, v6
	v_and_b32_e32 v6, 0xffff0000, v37
	ds_read_b128 v[34:37], v89 offset:13120
	v_and_b32_e32 v7, 0xffff0000, v41
	v_fma_f32 v6, v63, v6, v124
	v_fma_f32 v100, v107, v7, v6
	v_lshlrev_b32_e32 v7, 16, v30
	v_lshlrev_b32_e32 v6, 16, v26
	ds_read_b128 v[38:41], v89 offset:13152
	s_waitcnt lgkmcnt(1)
	v_fma_f32 v6, v96, v6, v125
	v_fma_f32 v106, v34, v7, v6
	v_and_b32_e32 v7, 0xffff0000, v30
	v_and_b32_e32 v6, 0xffff0000, v26
	v_fma_f32 v6, v97, v6, v126
	v_fma_f32 v103, v35, v7, v6
	v_lshlrev_b32_e32 v7, 16, v31
	v_lshlrev_b32_e32 v6, 16, v27
	v_fma_f32 v6, v98, v6, v127
	v_fma_f32 v102, v36, v7, v6
	v_and_b32_e32 v7, 0xffff0000, v31
	v_and_b32_e32 v6, 0xffff0000, v27
	v_fma_f32 v6, v99, v6, v128
	v_fma_f32 v99, v37, v7, v6
	v_lshlrev_b32_e32 v7, 16, v32
	v_lshlrev_b32_e32 v6, 16, v28
	s_waitcnt lgkmcnt(0)
	v_fma_f32 v6, v118, v6, v129
	v_fma_f32 v97, v38, v7, v6
	v_and_b32_e32 v7, 0xffff0000, v32
	v_and_b32_e32 v6, 0xffff0000, v28
	v_fma_f32 v6, v119, v6, v130
	v_fma_f32 v96, v39, v7, v6
	v_lshlrev_b32_e32 v7, 16, v33
	v_lshlrev_b32_e32 v6, 16, v29
	v_fma_f32 v6, v120, v6, v131
	v_fma_f32 v95, v40, v7, v6
	v_and_b32_e32 v6, 0xffff0000, v29
	ds_read_b128 v[26:29], v89 offset:13184
	v_and_b32_e32 v7, 0xffff0000, v33
	v_fma_f32 v6, v121, v6, v117
	v_fma_f32 v90, v41, v7, v6
	v_lshlrev_b32_e32 v7, 16, v22
	v_lshlrev_b32_e32 v6, 16, v18
	ds_read_b128 v[30:33], v89 offset:13216
	s_waitcnt lgkmcnt(1)
	v_fma_f32 v6, v46, v6, v132
	v_fma_f32 v91, v26, v7, v6
	v_and_b32_e32 v7, 0xffff0000, v22
	v_and_b32_e32 v6, 0xffff0000, v18
	v_fma_f32 v6, v47, v6, v133
	v_fma_f32 v107, v27, v7, v6
	v_lshlrev_b32_e32 v7, 16, v23
	v_lshlrev_b32_e32 v6, 16, v19
	v_fma_f32 v6, v48, v6, v92
	v_fma_f32 v108, v28, v7, v6
	v_and_b32_e32 v7, 0xffff0000, v23
	v_and_b32_e32 v6, 0xffff0000, v19
	s_or_b32 s4, s4, s45
	v_fma_f32 v6, v49, v6, v54
	v_fma_f32 v105, v29, v7, v6
	s_lshl_b32 s4, s4, 3
	s_ashr_i32 s5, s48, 31
	s_add_u32 s4, s48, s4
	v_lshlrev_b32_e32 v7, 16, v24
	v_lshlrev_b32_e32 v6, 16, v20
	s_waitcnt lgkmcnt(0)
	s_addc_u32 s5, s5, 0
	v_fma_f32 v6, v42, v6, v51
	v_fma_f32 v104, v30, v7, v6
	s_lshl_b64 s[4:5], s[4:5], 13
	s_add_u32 s4, s42, s4
	v_and_b32_e32 v7, 0xffff0000, v24
	v_and_b32_e32 v6, 0xffff0000, v20
	s_addc_u32 s5, s43, s5
	s_lshl_b32 s2, s2, 14
	v_fma_f32 v6, v43, v6, v52
	v_fma_f32 v101, v31, v7, v6
	s_add_u32 s48, s42, s2
	v_lshlrev_b32_e32 v0, 4, v86
	s_addc_u32 s49, s43, 0
	v_lshlrev_b32_e32 v7, 16, v25
	v_lshlrev_b32_e32 v6, 16, v21
	v_lshl_add_u64 v[38:39], s[48:49], 0, v[0:1]
	s_mov_b32 s2, 0x2501000
	v_fma_f32 v6, v44, v6, v50
	v_fma_f32 v98, v32, v7, v6
	v_add_co_u32_e32 v166, vcc, s2, v38
	s_nop 0
	v_addc_co_u32_e32 v167, vcc, 0, v39, vcc
	v_and_b32_e32 v7, 0xffff0000, v25
	v_and_b32_e32 v6, 0xffff0000, v21
	ds_read_b128 v[118:121], v89 offset:13248
	ds_read_b128 v[122:125], v89 offset:13280
	v_cvt_pk_bf16_f32 v126, v115, v114
	v_cvt_pk_bf16_f32 v127, v113, v112
	v_cvt_pk_bf16_f32 v128, v111, v110
	v_cvt_pk_bf16_f32 v129, v109, v100
	global_load_dwordx4 v[34:37], v[166:167], off offset:-4096
	global_load_dwordx4 v[130:133], v[166:167], off
	v_fma_f32 v6, v45, v6, v53
	v_fma_f32 v92, v33, v7, v6
	v_add_f32_e32 v117, v2, v3
	v_lshlrev_b32_e32 v3, 16, v8
	v_lshlrev_b32_e32 v2, 16, v4
	v_fma_f32 v2, v14, v2, v10
	v_fma_f32 v174, v74, v3, v2
	s_mov_b32 s2, 0x2503000
	v_and_b32_e32 v3, 0xffff0000, v8
	v_and_b32_e32 v2, 0xffff0000, v4
	v_mov_b32_e32 v74, v15
	v_add_co_u32_e32 v168, vcc, s2, v38
	v_pk_mul_f32 v[2:3], v[74:75], v[2:3]
	v_lshlrev_b32_e32 v19, 16, v70
	v_lshlrev_b32_e32 v18, 16, v66
	v_mov_b32_e32 v20, v82
	s_waitcnt lgkmcnt(1)
; __device__ __forceinline__ unsigned cvt_pk_bf16(float lo, float hi) { unsigned r; asm volatile("v_cvt_pk_bf16_f32 %0, %1, %2" : "=v"(r) : "v"(lo), "v"(hi)); return r; }
; __device__ __forceinline__ float sigm(float x) { return __builtin_amdgcn_rcpf(1.f + __expf(-x)); }
; #define GAS __attribute__((address_space(1)))
; #define LAS __attribute__((address_space(3)))
; template <int PASS>
; __device__ __forceinline__ void lru_unit(const LruPtrs& args, LAS unsigned char* lds, int chunk, int bl, int g, int ck) {
;     ...
;         const GAS bf16* wrf = (const GAS bf16*)(ws + WS_WRF) + (size_t)g * (2 * 2 * 4 * 64 * 8) + lane * 8;
; #pragma unroll
;         for (int ks = 0; ks < 4; ++ks) {
;             v4u bw; bw.x = pg8::cvt_pk_bf16(xc[2 * ks][0], xc[2 * ks][1]); bw.y = pg8::cvt_pk_bf16(xc[2 * ks][2], xc[2 * ks][3]); bw.z = pg8::cvt_pk_bf16(xc[2 * ks + 1][0], xc[2 * ks + 1][1]); bw.w = pg8::cvt_pk_bf16(xc[2 * ks + 1][2], xc[2 * ks + 1][3]);
;             const bf16x8 bfr = __builtin_bit_cast(bf16x8, bw);
; #pragma unroll
;             for (int rb = 0; rb < 2; ++rb) {
;                 const bf16x8 wr_ = __builtin_bit_cast(bf16x8, *(const GAS v4u*)(wrf + ((0 * 2 + rb) * 4 + ks) * 512));
;                 const bf16x8 wi_ = __builtin_bit_cast(bf16x8, *(const GAS v4u*)(wrf + ((1 * 2 + rb) * 4 + ks) * 512));
;                 ar[rb] = __builtin_amdgcn_mfma_f32_32x32x16_bf16(wr_, bfr, ar[rb], 0, 0, 0);
;                 ai_[rb] = __builtin_amdgcn_mfma_f32_32x32x16_bf16(wi_, bfr, ai_[rb], 0, 0, 0);
;             }
;         }
; #pragma unroll
;         for (int q = 0; q < 8; ++q) {
;             const f32x4 br = *(const LAS f32x4*)(PRM + 5 * 64 + 8 * q + 4 * hi), bi = *(const LAS f32x4*)(PRM + 6 * 64 + 8 * q + 4 * hi), cf = *(const LAS f32x4*)(PRM + 7 * 64 + 8 * q + 4 * hi);
; #pragma unroll
;             for (int p = 0; p < 4; ++p) { const int rb = q >> 2, r = (q & 3) * 4 + p;
;                 const float rr = pg8::sigm(ar[rb][r] + br[p]), ii = pg8::sigm(ai_[rb][r] + bi[p]);
;                 const float a0 = __builtin_amdgcn_exp2f(cf[p] * rr);
;                 av[q][p] = a0; uv[q][p] = __builtin_amdgcn_sqrtf(fmaxf(1.f - a0 * a0, 0.f)) * (ii * xc[q][p]); }
	v_mov_b32_e32 v21, v118
	v_addc_co_u32_e32 v169, vcc, 0, v39, vcc
	v_add_f32_e32 v2, v11, v2
	v_pk_mul_f32 v[18:19], v[20:21], v[18:19]
	global_load_dwordx4 v[56:59], v[168:169], off offset:-4096
	global_load_dwordx4 v[26:29], v[168:169], off
	v_cvt_pk_bf16_f32 v134, v106, v103
	v_cvt_pk_bf16_f32 v135, v102, v99
	v_cvt_pk_bf16_f32 v136, v97, v96
	v_cvt_pk_bf16_f32 v137, v95, v90
	global_load_dwordx4 v[146:149], v[166:167], off offset:1024
	global_load_dwordx4 v[150:153], v[168:169], off offset:1024
	v_add_f32_e32 v175, v2, v3
	v_lshlrev_b32_e32 v3, 16, v9
	v_lshlrev_b32_e32 v2, 16, v5
	v_add_f32_e32 v18, v94, v18
	v_fma_f32 v2, v16, v2, v12
	v_fma_f32 v176, v76, v3, v2
	v_add_f32_e32 v94, v18, v19
	v_and_b32_e32 v19, 0xffff0000, v70
	v_and_b32_e32 v18, 0xffff0000, v66
	v_mov_b32_e32 v118, v83
	v_pk_mul_f32 v[74:75], v[118:119], v[18:19]
	v_and_b32_e32 v3, 0xffff0000, v9
	v_and_b32_e32 v2, 0xffff0000, v5
	v_mov_b32_e32 v76, v17
	v_add_f32_e32 v66, v93, v74
	v_pk_mul_f32 v[2:3], v[76:77], v[2:3]
	v_add_f32_e32 v93, v66, v75
	v_lshlrev_b32_e32 v75, 16, v71
	v_lshlrev_b32_e32 v74, 16, v67
	s_mov_b32 s2, 0x2502000
	v_fma_f32 v66, v84, v74, v116
	v_fma_f32 v83, v120, v75, v66
	s_mov_b64 s[48:49], 0x2500000
	v_add_co_u32_e32 v172, vcc, s2, v38
	v_and_b32_e32 v71, 0xffff0000, v71
	v_and_b32_e32 v70, 0xffff0000, v67
	v_lshl_add_u64 v[170:171], v[38:39], 0, s[48:49]
	v_addc_co_u32_e32 v173, vcc, 0, v39, vcc
	v_fma_f32 v66, v85, v70, v117
	v_fma_f32 v82, v121, v71, v66
	global_load_dwordx4 v[138:141], v[170:171], off offset:1024
	global_load_dwordx4 v[142:145], v[172:173], off offset:1024
	v_cvt_pk_bf16_f32 v154, v91, v107
	v_cvt_pk_bf16_f32 v155, v108, v105
	v_cvt_pk_bf16_f32 v156, v104, v101
	v_cvt_pk_bf16_f32 v157, v98, v92
	global_load_dwordx4 v[116:119], v[166:167], off offset:2048
	v_lshlrev_b32_e32 v67, 16, v72
	v_lshlrev_b32_e32 v66, 16, v68
	s_waitcnt lgkmcnt(0)
	v_fma_f32 v66, v78, v66, v174
	v_fma_f32 v77, v122, v67, v66
	v_and_b32_e32 v67, 0xffff0000, v72
	v_and_b32_e32 v66, 0xffff0000, v68
	v_fma_f32 v66, v79, v66, v175
	v_fma_f32 v76, v123, v67, v66
	global_load_dwordx4 v[120:123], v[168:169], off offset:2048
	global_load_dwordx4 v[158:161], v[170:171], off offset:2048
	global_load_dwordx4 v[162:165], v[172:173], off offset:2048
	v_lshlrev_b32_e32 v67, 16, v73
	v_lshlrev_b32_e32 v66, 16, v69
	v_fma_f32 v66, v80, v66, v176
	v_fma_f32 v74, v124, v67, v66
	v_add_f32_e32 v2, v13, v2
	v_and_b32_e32 v67, 0xffff0000, v73
	v_and_b32_e32 v66, 0xffff0000, v69
	v_mov_b32_e32 v124, v81
	v_add_f32_e32 v177, v2, v3
	s_waitcnt vmcnt(10)
	v_mfma_f32_32x32x16_bf16 v[2:17], v[130:133], v[126:129], 0
	v_mul_f32_e64 v66, v124, v66
	v_mul_f32_e64 v67, v125, v67
	v_cvt_pk_bf16_f32 v78, v94, v93
	v_cvt_pk_bf16_f32 v79, v83, v82
	v_cvt_pk_bf16_f32 v80, v77, v76
	s_mov_b32 s2, 0x29c01000
	v_add_f32_e32 v66, v177, v66
	v_add_f32_e32 v75, v66, v67
	v_cvt_pk_bf16_f32 v81, v74, v75
	global_load_dwordx4 v[66:69], v[170:171], off offset:3072
	global_load_dwordx4 v[70:73], v[172:173], off offset:3072
	s_waitcnt vmcnt(9)
	v_mfma_f32_32x32x16_bf16 v[2:17], v[146:149], v[134:137], v[2:17]
	s_waitcnt vmcnt(5)
	v_mfma_f32_32x32x16_bf16 v[2:17], v[116:119], v[154:157], v[2:17]
	global_load_dwordx4 v[116:119], v[166:167], off offset:3072
	v_mfma_f32_32x32x16_bf16 v[18:33], v[26:29], v[126:129], 0
	v_mfma_f32_32x32x16_bf16 v[34:49], v[34:37], v[126:129], 0
	v_mfma_f32_32x32x16_bf16 v[18:33], v[150:153], v[134:137], v[18:33]
	v_mfma_f32_32x32x16_bf16 v[50:65], v[56:59], v[126:129], 0
	ds_read_b128 v[124:127], v89 offset:13568
	ds_read_b128 v[128:131], v89 offset:13600
	v_mfma_f32_32x32x16_bf16 v[34:49], v[138:141], v[134:137], v[34:49]
	s_waitcnt vmcnt(5)
	v_mfma_f32_32x32x16_bf16 v[18:33], v[120:123], v[154:157], v[18:33]
	global_load_dwordx4 v[120:123], v[168:169], off offset:3072
	v_mfma_f32_32x32x16_bf16 v[50:65], v[142:145], v[134:137], v[50:65]
	s_waitcnt vmcnt(5)
	v_mfma_f32_32x32x16_bf16 v[34:49], v[158:161], v[154:157], v[34:49]
	s_waitcnt vmcnt(4)
	v_mfma_f32_32x32x16_bf16 v[50:65], v[162:165], v[154:157], v[50:65]
	s_waitcnt vmcnt(3)
	v_mfma_f32_32x32x16_bf16 v[34:49], v[66:69], v[78:81], v[34:49]
	s_waitcnt vmcnt(2)
	v_mfma_f32_32x32x16_bf16 v[50:65], v[70:73], v[78:81], v[50:65]
	v_lshl_add_u64 v[72:73], s[4:5], 0, v[0:1]
	s_waitcnt lgkmcnt(1)
	s_nop 7
	v_add_f32_e32 v0, v34, v124
	v_mul_f32_e32 v0, 0xbfb8aa3b, v0
	v_exp_f32_e32 v0, v0
	v_add_f32_e32 v35, v35, v125
	v_mul_f32_e32 v35, 0xbfb8aa3b, v35
	v_exp_f32_e32 v35, v35
	s_waitcnt vmcnt(1)
	v_mfma_f32_32x32x16_bf16 v[2:17], v[116:119], v[78:81], v[2:17]
	ds_read_b128 v[116:119], v89 offset:13824
	ds_read_b128 v[132:135], v89 offset:14080
	v_add_f32_e32 v0, 1.0, v0
	v_rcp_f32_e32 v0, v0
	v_add_f32_e32 v35, 1.0, v35
	s_waitcnt lgkmcnt(1)
	v_add_f32_e32 v34, v50, v116
	v_mul_f32_e32 v34, 0xbfb8aa3b, v34
	s_waitcnt lgkmcnt(0)
; __device__ __forceinline__ float sigm(float x) { return __builtin_amdgcn_rcpf(1.f + __expf(-x)); }
; #define LAS __attribute__((address_space(3)))
; template <int PASS>
; __device__ __forceinline__ void lru_unit(const LruPtrs& args, LAS unsigned char* lds, int chunk, int bl, int g, int ck) {
;     ...
; #pragma unroll
;         for (int q = 0; q < 8; ++q) {
;             const f32x4 br = *(const LAS f32x4*)(PRM + 5 * 64 + 8 * q + 4 * hi), bi = *(const LAS f32x4*)(PRM + 6 * 64 + 8 * q + 4 * hi), cf = *(const LAS f32x4*)(PRM + 7 * 64 + 8 * q + 4 * hi);
; #pragma unroll
;             for (int p = 0; p < 4; ++p) { const int rb = q >> 2, r = (q & 3) * 4 + p;
;                 const float rr = pg8::sigm(ar[rb][r] + br[p]), ii = pg8::sigm(ai_[rb][r] + bi[p]);
;                 const float a0 = __builtin_amdgcn_exp2f(cf[p] * rr);
;                 av[q][p] = a0; uv[q][p] = __builtin_amdgcn_sqrtf(fmaxf(1.f - a0 * a0, 0.f)) * (ii * xc[q][p]); }
	v_mul_f32_e32 v0, v132, v0
	v_exp_f32_e32 v34, v34
	v_exp_f32_e32 v66, v0
	v_rcp_f32_e32 v35, v35
	v_add_f32_e32 v50, v51, v117
	v_add_f32_e32 v0, 1.0, v34
	v_fma_f32 v34, -v66, v66, 1.0
	v_rcp_f32_e32 v0, v0
	v_max_f32_e32 v34, 0, v34
	v_mul_f32_e32 v50, 0xbfb8aa3b, v50
	v_mul_f32_e32 v35, v133, v35
	v_sqrt_f32_e32 v34, v34
	v_exp_f32_e32 v50, v50
	v_exp_f32_e32 v68, v35
	v_mul_f32_e32 v0, v115, v0
	v_mul_f32_e32 v67, v0, v34
	v_add_f32_e32 v0, 1.0, v50
	v_fma_f32 v34, -v68, v68, 1.0
	v_add_f32_e32 v35, v36, v126
	v_rcp_f32_e32 v0, v0
	v_mul_f32_e32 v35, 0xbfb8aa3b, v35
	v_max_f32_e32 v34, 0, v34
	v_exp_f32_e32 v35, v35
	v_sqrt_f32_e32 v36, v34
	v_mul_f32_e32 v0, v114, v0
	v_add_f32_e32 v38, v38, v128
	v_add_f32_e32 v34, 1.0, v35
	v_mul_f32_e32 v69, v0, v36
	v_add_f32_e32 v36, v37, v127
	v_rcp_f32_e32 v34, v34
	v_mul_f32_e32 v36, 0xbfb8aa3b, v36
	v_exp_f32_e32 v36, v36
	v_add_f32_e32 v35, v52, v118
	v_mul_f32_e32 v35, 0xbfb8aa3b, v35
	v_mul_f32_e32 v34, v134, v34
	v_exp_f32_e32 v35, v35
	v_exp_f32_e32 v34, v34
	v_add_f32_e32 v36, 1.0, v36
	v_rcp_f32_e32 v36, v36
	v_mul_f32_e32 v38, 0xbfb8aa3b, v38
	v_exp_f32_e32 v38, v38
	v_add_f32_e32 v0, 1.0, v35
	v_fma_f32 v35, -v34, v34, 1.0
	v_add_f32_e32 v37, v53, v119
	ds_read_b128 v[136:139], v89 offset:13856
	ds_read_b128 v[140:143], v89 offset:14112
	v_rcp_f32_e32 v0, v0
	v_max_f32_e32 v35, 0, v35
	v_mul_f32_e32 v37, 0xbfb8aa3b, v37
	v_mul_f32_e32 v36, v135, v36
	v_sqrt_f32_e32 v35, v35
	v_exp_f32_e32 v37, v37
	v_exp_f32_e32 v36, v36
	v_add_f32_e32 v38, 1.0, v38
	v_add_f32_e32 v39, v39, v129
	v_rcp_f32_e32 v38, v38
	v_mul_f32_e32 v39, 0xbfb8aa3b, v39
	v_exp_f32_e32 v39, v39
	v_mul_f32_e32 v0, v113, v0
	v_mul_f32_e32 v35, v0, v35
	v_add_f32_e32 v0, 1.0, v37
	v_fma_f32 v37, -v36, v36, 1.0
	s_waitcnt lgkmcnt(1)
	v_add_f32_e32 v50, v54, v136
	v_rcp_f32_e32 v0, v0
	v_max_f32_e32 v37, 0, v37
	v_mul_f32_e32 v50, 0xbfb8aa3b, v50
	s_waitcnt lgkmcnt(0)
	v_mul_f32_e32 v38, v140, v38
	v_sqrt_f32_e32 v37, v37
	v_exp_f32_e32 v51, v50
	v_exp_f32_e32 v50, v38
	v_add_f32_e32 v39, 1.0, v39
	v_rcp_f32_e32 v39, v39
	v_mul_f32_e32 v0, v112, v0
	v_mul_f32_e32 v37, v0, v37
	v_add_f32_e32 v0, 1.0, v51
	v_fma_f32 v38, -v50, v50, 1.0
	v_rcp_f32_e32 v0, v0
	v_max_f32_e32 v38, 0, v38
	v_add_f32_e32 v51, v55, v137
	v_mul_f32_e32 v39, v141, v39
	v_sqrt_f32_e32 v38, v38
	v_mul_f32_e32 v51, 0xbfb8aa3b, v51
	v_exp_f32_e32 v52, v39
	v_add_f32_e32 v39, v40, v130
	v_exp_f32_e32 v53, v51
	v_mul_f32_e32 v39, 0xbfb8aa3b, v39
	v_exp_f32_e32 v39, v39
	v_mul_f32_e32 v0, v111, v0
	v_mul_f32_e32 v51, v0, v38
	v_fma_f32 v38, -v52, v52, 1.0
	v_add_f32_e32 v0, 1.0, v53
	v_max_f32_e32 v38, 0, v38
	v_rcp_f32_e32 v0, v0
	v_sqrt_f32_e32 v40, v38
	v_add_f32_e32 v38, 1.0, v39
	v_rcp_f32_e32 v38, v38
	v_mul_f32_e32 v0, v110, v0
	v_add_f32_e32 v39, v56, v138
	v_mul_f32_e32 v39, 0xbfb8aa3b, v39
	v_mul_f32_e32 v38, v142, v38
	v_mul_f32_e32 v53, v0, v40
	v_add_f32_e32 v40, v41, v131
	s_waitcnt vmcnt(0)
	v_mfma_f32_32x32x16_bf16 v[18:33], v[120:123], v[78:81], v[18:33]
	v_exp_f32_e32 v39, v39
	v_exp_f32_e32 v38, v38
	v_mul_f32_e32 v40, 0xbfb8aa3b, v40
	ds_read_b128 v[78:81], v89 offset:13632
	ds_read_b128 v[110:113], v89 offset:13664
	v_exp_f32_e32 v40, v40
	v_add_f32_e32 v0, 1.0, v39
	v_fma_f32 v39, -v38, v38, 1.0
	v_rcp_f32_e32 v0, v0
	v_max_f32_e32 v39, 0, v39
	v_add_f32_e32 v40, 1.0, v40
	s_waitcnt lgkmcnt(1)
	v_add_f32_e32 v42, v42, v78
	v_sqrt_f32_e32 v39, v39
	v_rcp_f32_e32 v40, v40
	v_mul_f32_e32 v42, 0xbfb8aa3b, v42
	v_exp_f32_e32 v42, v42
	v_mul_f32_e32 v0, v109, v0
	v_add_f32_e32 v41, v57, v139
	v_mul_f32_e32 v41, 0xbfb8aa3b, v41
	v_mul_f32_e32 v39, v0, v39
	v_mul_f32_e32 v0, v143, v40
	v_exp_f32_e32 v41, v41
	v_exp_f32_e32 v40, v0
	ds_read_b128 v[114:117], v89 offset:13888
	ds_read_b128 v[118:121], v89 offset:14144
	v_add_f32_e32 v42, 1.0, v42
	v_add_f32_e32 v43, v43, v79
	v_rcp_f32_e32 v42, v42
	v_mul_f32_e32 v43, 0xbfb8aa3b, v43
	v_exp_f32_e32 v43, v43
	v_add_f32_e32 v0, 1.0, v41
	v_fma_f32 v41, -v40, v40, 1.0
	s_waitcnt lgkmcnt(1)
	v_add_f32_e32 v54, v58, v114
	v_rcp_f32_e32 v0, v0
	v_max_f32_e32 v41, 0, v41
	v_mul_f32_e32 v54, 0xbfb8aa3b, v54
	s_waitcnt lgkmcnt(0)
	v_mul_f32_e32 v42, v118, v42
	v_sqrt_f32_e32 v41, v41
	v_exp_f32_e32 v55, v54
	v_exp_f32_e32 v54, v42
	v_add_f32_e32 v43, 1.0, v43
	v_rcp_f32_e32 v43, v43
	v_mul_f32_e32 v0, v100, v0
	v_mul_f32_e32 v41, v0, v41
	v_add_f32_e32 v0, 1.0, v55
	v_fma_f32 v42, -v54, v54, 1.0
	v_add_f32_e32 v55, v59, v115
	v_rcp_f32_e32 v0, v0
	v_max_f32_e32 v42, 0, v42
	v_mul_f32_e32 v55, 0xbfb8aa3b, v55
	v_mul_f32_e32 v43, v119, v43
	v_sqrt_f32_e32 v42, v42
	v_exp_f32_e32 v57, v55
	v_exp_f32_e32 v56, v43
	v_mul_f32_e32 v0, v106, v0
	v_mul_f32_e32 v55, v0, v42
	v_add_f32_e32 v0, 1.0, v57
	v_fma_f32 v42, -v56, v56, 1.0
	v_add_f32_e32 v43, v44, v80
	v_rcp_f32_e32 v0, v0
	v_mul_f32_e32 v43, 0xbfb8aa3b, v43
	v_max_f32_e32 v42, 0, v42
	v_exp_f32_e32 v43, v43
	v_sqrt_f32_e32 v44, v42
	v_mul_f32_e32 v0, v103, v0
	v_add_f32_e32 v46, v46, v110
	v_add_f32_e32 v42, 1.0, v43
	v_mul_f32_e32 v57, v0, v44
	v_add_f32_e32 v44, v45, v81
	v_rcp_f32_e32 v42, v42
	v_mul_f32_e32 v44, 0xbfb8aa3b, v44
	v_exp_f32_e32 v44, v44
	v_add_f32_e32 v43, v60, v116
	v_mul_f32_e32 v43, 0xbfb8aa3b, v43
	v_mul_f32_e32 v42, v120, v42
	v_exp_f32_e32 v43, v43
	v_exp_f32_e32 v42, v42
	v_add_f32_e32 v44, 1.0, v44
	v_rcp_f32_e32 v44, v44
	v_mul_f32_e32 v46, 0xbfb8aa3b, v46
	v_exp_f32_e32 v46, v46
	v_add_f32_e32 v0, 1.0, v43
	v_fma_f32 v43, -v42, v42, 1.0
	v_add_f32_e32 v45, v61, v117
	ds_read_b128 v[122:125], v89 offset:13920
	ds_read_b128 v[126:129], v89 offset:14176
	v_rcp_f32_e32 v0, v0
	v_max_f32_e32 v43, 0, v43
	v_mul_f32_e32 v45, 0xbfb8aa3b, v45
	v_mul_f32_e32 v44, v121, v44
	v_sqrt_f32_e32 v43, v43
	v_exp_f32_e32 v45, v45
	v_exp_f32_e32 v44, v44
	v_add_f32_e32 v46, 1.0, v46
	v_add_f32_e32 v47, v47, v111
	v_rcp_f32_e32 v46, v46
	v_mul_f32_e32 v47, 0xbfb8aa3b, v47
	v_exp_f32_e32 v47, v47
	v_mul_f32_e32 v0, v102, v0
	v_mul_f32_e32 v43, v0, v43
	v_add_f32_e32 v0, 1.0, v45
	v_fma_f32 v45, -v44, v44, 1.0
	s_waitcnt lgkmcnt(1)
; __device__ __forceinline__ float sigm(float x) { return __builtin_amdgcn_rcpf(1.f + __expf(-x)); }
; #define LAS __attribute__((address_space(3)))
; template <int PASS>
; __device__ __forceinline__ void lru_unit(const LruPtrs& args, LAS unsigned char* lds, int chunk, int bl, int g, int ck) {
;     ...
; #pragma unroll
;         for (int q = 0; q < 8; ++q) {
;             const f32x4 br = *(const LAS f32x4*)(PRM + 5 * 64 + 8 * q + 4 * hi), bi = *(const LAS f32x4*)(PRM + 6 * 64 + 8 * q + 4 * hi), cf = *(const LAS f32x4*)(PRM + 7 * 64 + 8 * q + 4 * hi);
; #pragma unroll
;             for (int p = 0; p < 4; ++p) { const int rb = q >> 2, r = (q & 3) * 4 + p;
;                 const float rr = pg8::sigm(ar[rb][r] + br[p]), ii = pg8::sigm(ai_[rb][r] + bi[p]);
;                 const float a0 = __builtin_amdgcn_exp2f(cf[p] * rr);
;                 av[q][p] = a0; uv[q][p] = __builtin_amdgcn_sqrtf(fmaxf(1.f - a0 * a0, 0.f)) * (ii * xc[q][p]); }
	v_add_f32_e32 v58, v62, v122
	v_rcp_f32_e32 v0, v0
	v_max_f32_e32 v45, 0, v45
	v_mul_f32_e32 v58, 0xbfb8aa3b, v58
	s_waitcnt lgkmcnt(0)
	v_mul_f32_e32 v46, v126, v46
	v_sqrt_f32_e32 v45, v45
	v_exp_f32_e32 v59, v58
	v_exp_f32_e32 v58, v46
	v_add_f32_e32 v47, 1.0, v47
	v_rcp_f32_e32 v47, v47
	v_mul_f32_e32 v0, v99, v0
	v_mul_f32_e32 v45, v0, v45
	v_add_f32_e32 v0, 1.0, v59
	v_fma_f32 v46, -v58, v58, 1.0
	v_rcp_f32_e32 v0, v0
	v_max_f32_e32 v46, 0, v46
	v_add_f32_e32 v59, v63, v123
	v_mul_f32_e32 v47, v127, v47
	v_sqrt_f32_e32 v46, v46
	v_mul_f32_e32 v59, 0xbfb8aa3b, v59
	v_exp_f32_e32 v60, v47
	v_add_f32_e32 v47, v48, v112
	v_exp_f32_e32 v61, v59
	v_mul_f32_e32 v47, 0xbfb8aa3b, v47
	v_exp_f32_e32 v47, v47
	v_mul_f32_e32 v0, v97, v0
	v_mul_f32_e32 v59, v0, v46
	v_fma_f32 v46, -v60, v60, 1.0
	v_add_f32_e32 v0, 1.0, v61
	v_max_f32_e32 v46, 0, v46
	v_rcp_f32_e32 v0, v0
	v_sqrt_f32_e32 v48, v46
	v_add_f32_e32 v46, 1.0, v47
	v_rcp_f32_e32 v46, v46
	v_mul_f32_e32 v0, v96, v0
	v_add_f32_e32 v47, v64, v124
	v_mul_f32_e32 v47, 0xbfb8aa3b, v47
	v_mul_f32_e32 v46, v128, v46
	v_mul_f32_e32 v61, v0, v48
	v_add_f32_e32 v48, v49, v113
	v_exp_f32_e32 v47, v47
	v_exp_f32_e32 v46, v46
	v_mul_f32_e32 v48, 0xbfb8aa3b, v48
	ds_read_b128 v[78:81], v89 offset:13696
	ds_read_b128 v[110:113], v89 offset:13728
	v_exp_f32_e32 v48, v48
	v_add_f32_e32 v0, 1.0, v47
	v_fma_f32 v47, -v46, v46, 1.0
	v_rcp_f32_e32 v0, v0
	v_max_f32_e32 v47, 0, v47
	v_add_f32_e32 v48, 1.0, v48
	s_waitcnt lgkmcnt(1)
	v_add_f32_e32 v2, v2, v78
	v_sqrt_f32_e32 v47, v47
	v_rcp_f32_e32 v48, v48
	v_mul_f32_e32 v2, 0xbfb8aa3b, v2
	v_exp_f32_e32 v2, v2
	v_mul_f32_e32 v0, v95, v0
	v_add_f32_e32 v49, v65, v125
	v_mul_f32_e32 v49, 0xbfb8aa3b, v49
	v_mul_f32_e32 v47, v0, v47
	v_mul_f32_e32 v0, v129, v48
	v_exp_f32_e32 v49, v49
	v_exp_f32_e32 v48, v0
	ds_read_b128 v[114:117], v89 offset:13952
	ds_read_b128 v[118:121], v89 offset:14208
	v_add_f32_e32 v2, 1.0, v2
	v_add_f32_e32 v3, v3, v79
	v_rcp_f32_e32 v2, v2
	v_mul_f32_e32 v3, 0xbfb8aa3b, v3
	v_exp_f32_e32 v3, v3
	v_add_f32_e32 v0, 1.0, v49
	v_fma_f32 v49, -v48, v48, 1.0
	s_waitcnt lgkmcnt(1)
	v_add_f32_e32 v18, v18, v114
	v_rcp_f32_e32 v0, v0
	v_max_f32_e32 v49, 0, v49
	v_mul_f32_e32 v18, 0xbfb8aa3b, v18
	s_waitcnt lgkmcnt(0)
	v_mul_f32_e32 v2, v118, v2
	v_sqrt_f32_e32 v49, v49
	v_exp_f32_e32 v18, v18
	v_exp_f32_e32 v62, v2
	v_add_f32_e32 v3, 1.0, v3
	v_rcp_f32_e32 v3, v3
	v_mul_f32_e32 v0, v90, v0
	v_mul_f32_e32 v49, v0, v49
	v_add_f32_e32 v0, 1.0, v18
	v_fma_f32 v2, -v62, v62, 1.0
	v_add_f32_e32 v18, v19, v115
	v_rcp_f32_e32 v0, v0
	v_max_f32_e32 v2, 0, v2
	v_mul_f32_e32 v18, 0xbfb8aa3b, v18
	v_mul_f32_e32 v3, v119, v3
	v_sqrt_f32_e32 v2, v2
	v_exp_f32_e32 v18, v18
	v_exp_f32_e32 v64, v3
	v_mul_f32_e32 v0, v91, v0
	v_mul_f32_e32 v63, v0, v2
	v_add_f32_e32 v0, 1.0, v18
	v_fma_f32 v2, -v64, v64, 1.0
	v_add_f32_e32 v3, v4, v80
	v_rcp_f32_e32 v0, v0
	v_mul_f32_e32 v3, 0xbfb8aa3b, v3
	v_max_f32_e32 v2, 0, v2
	v_exp_f32_e32 v3, v3
	v_sqrt_f32_e32 v4, v2
	v_mul_f32_e32 v0, v107, v0
	v_add_f32_e32 v6, v6, v110
	v_add_f32_e32 v2, 1.0, v3
	v_mul_f32_e32 v65, v0, v4
	v_add_f32_e32 v4, v5, v81
	v_rcp_f32_e32 v2, v2
	v_mul_f32_e32 v4, 0xbfb8aa3b, v4
	v_exp_f32_e32 v4, v4
	v_add_f32_e32 v3, v20, v116
	v_mul_f32_e32 v3, 0xbfb8aa3b, v3
	v_mul_f32_e32 v2, v120, v2
	v_exp_f32_e32 v3, v3
	v_exp_f32_e32 v2, v2
	v_add_f32_e32 v4, 1.0, v4
	v_rcp_f32_e32 v4, v4
	v_mul_f32_e32 v6, 0xbfb8aa3b, v6
	v_exp_f32_e32 v6, v6
	v_add_f32_e32 v0, 1.0, v3
	v_fma_f32 v3, -v2, v2, 1.0
	v_add_f32_e32 v5, v21, v117
	ds_read_b128 v[122:125], v89 offset:13984
	ds_read_b128 v[126:129], v89 offset:14240
	v_rcp_f32_e32 v0, v0
	v_max_f32_e32 v3, 0, v3
	v_mul_f32_e32 v5, 0xbfb8aa3b, v5
	v_mul_f32_e32 v4, v121, v4
	v_sqrt_f32_e32 v3, v3
	v_exp_f32_e32 v5, v5
	v_exp_f32_e32 v4, v4
	v_add_f32_e32 v6, 1.0, v6
	v_add_f32_e32 v7, v7, v111
	v_rcp_f32_e32 v6, v6
	v_mul_f32_e32 v7, 0xbfb8aa3b, v7
	v_exp_f32_e32 v7, v7
	v_mul_f32_e32 v0, v108, v0
	v_mul_f32_e32 v3, v0, v3
	v_add_f32_e32 v0, 1.0, v5
	v_fma_f32 v5, -v4, v4, 1.0
	s_waitcnt lgkmcnt(1)
	v_add_f32_e32 v18, v22, v122
	v_rcp_f32_e32 v0, v0
	v_max_f32_e32 v5, 0, v5
	v_mul_f32_e32 v18, 0xbfb8aa3b, v18
	s_waitcnt lgkmcnt(0)
	v_mul_f32_e32 v6, v126, v6
	v_sqrt_f32_e32 v5, v5
	v_exp_f32_e32 v19, v18
	v_exp_f32_e32 v18, v6
	v_add_f32_e32 v7, 1.0, v7
	v_rcp_f32_e32 v7, v7
	v_mul_f32_e32 v0, v105, v0
	v_mul_f32_e32 v5, v0, v5
	v_add_f32_e32 v0, 1.0, v19
	v_fma_f32 v6, -v18, v18, 1.0
	v_rcp_f32_e32 v0, v0
	v_max_f32_e32 v6, 0, v6
	v_add_f32_e32 v19, v23, v123
	v_mul_f32_e32 v7, v127, v7
	v_sqrt_f32_e32 v6, v6
	v_mul_f32_e32 v19, 0xbfb8aa3b, v19
	v_exp_f32_e32 v20, v7
	v_add_f32_e32 v7, v8, v112
	v_exp_f32_e32 v21, v19
	v_mul_f32_e32 v7, 0xbfb8aa3b, v7
	v_exp_f32_e32 v7, v7
	v_mul_f32_e32 v0, v104, v0
	v_mul_f32_e32 v19, v0, v6
	v_fma_f32 v6, -v20, v20, 1.0
	v_add_f32_e32 v0, 1.0, v21
	v_max_f32_e32 v6, 0, v6
	v_rcp_f32_e32 v0, v0
	v_sqrt_f32_e32 v8, v6
	v_add_f32_e32 v6, 1.0, v7
	v_add_f32_e32 v7, v24, v124
	v_rcp_f32_e32 v6, v6
	v_mul_f32_e32 v7, 0xbfb8aa3b, v7
	v_exp_f32_e32 v7, v7
	v_mul_f32_e32 v0, v101, v0
	v_mul_f32_e32 v6, v128, v6
	v_mul_f32_e32 v21, v0, v8
	v_add_f32_e32 v8, v9, v113
	v_exp_f32_e32 v6, v6
	v_add_f32_e32 v0, 1.0, v7
	v_mul_f32_e32 v8, 0xbfb8aa3b, v8
	ds_read_b128 v[78:81], v89 offset:13760
	v_rcp_f32_e32 v0, v0
	v_exp_f32_e32 v8, v8
	v_fma_f32 v7, -v6, v6, 1.0
	v_max_f32_e32 v7, 0, v7
	v_mul_f32_e32 v0, v98, v0
	v_add_f32_e32 v8, 1.0, v8
	ds_read_b128 v[96:99], v89 offset:13792
	s_waitcnt lgkmcnt(1)
; __device__ __forceinline__ float sigm(float x) { return __builtin_amdgcn_rcpf(1.f + __expf(-x)); }
; #define LAS __attribute__((address_space(3)))
; template <int PASS>
; __device__ __forceinline__ void lru_unit(const LruPtrs& args, LAS unsigned char* lds, int chunk, int bl, int g, int ck) {
;     ...
; #pragma unroll
;         for (int q = 0; q < 8; ++q) {
;             const f32x4 br = *(const LAS f32x4*)(PRM + 5 * 64 + 8 * q + 4 * hi), bi = *(const LAS f32x4*)(PRM + 6 * 64 + 8 * q + 4 * hi), cf = *(const LAS f32x4*)(PRM + 7 * 64 + 8 * q + 4 * hi);
; #pragma unroll
;             for (int p = 0; p < 4; ++p) { const int rb = q >> 2, r = (q & 3) * 4 + p;
;                 const float rr = pg8::sigm(ar[rb][r] + br[p]), ii = pg8::sigm(ai_[rb][r] + bi[p]);
;                 const float a0 = __builtin_amdgcn_exp2f(cf[p] * rr);
;                 av[q][p] = a0; uv[q][p] = __builtin_amdgcn_sqrtf(fmaxf(1.f - a0 * a0, 0.f)) * (ii * xc[q][p]); }
	v_add_f32_e32 v10, v10, v78
	v_sqrt_f32_e32 v7, v7
	v_rcp_f32_e32 v8, v8
	v_mul_f32_e32 v10, 0xbfb8aa3b, v10
	v_exp_f32_e32 v10, v10
	v_add_f32_e32 v9, v25, v125
	v_mul_f32_e32 v9, 0xbfb8aa3b, v9
	v_mul_f32_e32 v7, v0, v7
	v_mul_f32_e32 v0, v129, v8
	v_exp_f32_e32 v9, v9
	v_exp_f32_e32 v8, v0
	ds_read_b128 v[100:103], v89 offset:14016
	ds_read_b128 v[104:107], v89 offset:14272
	v_add_f32_e32 v10, 1.0, v10
	v_add_f32_e32 v11, v11, v79
	v_rcp_f32_e32 v10, v10
	v_mul_f32_e32 v11, 0xbfb8aa3b, v11
	v_exp_f32_e32 v11, v11
	v_add_f32_e32 v0, 1.0, v9
	v_fma_f32 v9, -v8, v8, 1.0
	s_waitcnt lgkmcnt(1)
	v_add_f32_e32 v22, v26, v100
	v_rcp_f32_e32 v0, v0
	v_max_f32_e32 v9, 0, v9
	v_mul_f32_e32 v22, 0xbfb8aa3b, v22
	s_waitcnt lgkmcnt(0)
	v_mul_f32_e32 v10, v104, v10
	v_sqrt_f32_e32 v9, v9
	v_exp_f32_e32 v23, v22
	v_exp_f32_e32 v22, v10
	v_add_f32_e32 v11, 1.0, v11
	v_rcp_f32_e32 v11, v11
	v_mul_f32_e32 v0, v92, v0
	v_mul_f32_e32 v9, v0, v9
	v_add_f32_e32 v0, 1.0, v23
	v_fma_f32 v10, -v22, v22, 1.0
	v_add_f32_e32 v23, v27, v101
	v_rcp_f32_e32 v0, v0
	v_max_f32_e32 v10, 0, v10
	v_mul_f32_e32 v23, 0xbfb8aa3b, v23
	v_mul_f32_e32 v11, v105, v11
	v_sqrt_f32_e32 v10, v10
	v_exp_f32_e32 v25, v23
	v_exp_f32_e32 v24, v11
	v_mul_f32_e32 v0, v94, v0
	v_mul_f32_e32 v23, v0, v10
	v_add_f32_e32 v0, 1.0, v25
	v_fma_f32 v10, -v24, v24, 1.0
	v_add_f32_e32 v11, v12, v80
	v_rcp_f32_e32 v0, v0
	v_mul_f32_e32 v11, 0xbfb8aa3b, v11
	v_max_f32_e32 v10, 0, v10
	v_exp_f32_e32 v11, v11
	v_sqrt_f32_e32 v12, v10
	v_mul_f32_e32 v0, v93, v0
	v_add_f32_e32 v14, v14, v96
	v_add_f32_e32 v10, 1.0, v11
	v_mul_f32_e32 v25, v0, v12
	v_add_f32_e32 v12, v13, v81
	v_rcp_f32_e32 v10, v10
	v_mul_f32_e32 v12, 0xbfb8aa3b, v12
	v_exp_f32_e32 v12, v12
	v_add_f32_e32 v11, v28, v102
	v_mul_f32_e32 v11, 0xbfb8aa3b, v11
	v_mul_f32_e32 v10, v106, v10
	v_exp_f32_e32 v11, v11
	v_exp_f32_e32 v10, v10
	v_add_f32_e32 v12, 1.0, v12
	v_rcp_f32_e32 v12, v12
	v_mul_f32_e32 v14, 0xbfb8aa3b, v14
	v_exp_f32_e32 v14, v14
	v_add_f32_e32 v0, 1.0, v11
	v_fma_f32 v11, -v10, v10, 1.0
	v_add_f32_e32 v13, v29, v103
	ds_read_b128 v[108:111], v89 offset:14048
	ds_read_b128 v[112:115], v89 offset:14304
	v_rcp_f32_e32 v0, v0
	v_max_f32_e32 v11, 0, v11
	v_mul_f32_e32 v13, 0xbfb8aa3b, v13
	v_mul_f32_e32 v12, v107, v12
	v_sqrt_f32_e32 v11, v11
	v_exp_f32_e32 v13, v13
	v_exp_f32_e32 v12, v12
	v_add_f32_e32 v14, 1.0, v14
	v_rcp_f32_e32 v14, v14
	v_mul_f32_e32 v0, v83, v0
	v_mul_f32_e32 v11, v0, v11
	v_add_f32_e32 v0, 1.0, v13
	v_fma_f32 v13, -v12, v12, 1.0
	s_waitcnt lgkmcnt(1)
	v_add_f32_e32 v26, v30, v108
	v_rcp_f32_e32 v0, v0
	v_max_f32_e32 v13, 0, v13
	v_mul_f32_e32 v26, 0xbfb8aa3b, v26
	s_waitcnt lgkmcnt(0)
; __device__ __forceinline__ float sigm(float x) { return __builtin_amdgcn_rcpf(1.f + __expf(-x)); }
; #define LAS __attribute__((address_space(3)))
; template <int PASS>
; __device__ __forceinline__ void lru_unit(const LruPtrs& args, LAS unsigned char* lds, int chunk, int bl, int g, int ck) {
;     ...
; #pragma unroll
;         for (int q = 0; q < 8; ++q) {
;             const f32x4 br = *(const LAS f32x4*)(PRM + 5 * 64 + 8 * q + 4 * hi), bi = *(const LAS f32x4*)(PRM + 6 * 64 + 8 * q + 4 * hi), cf = *(const LAS f32x4*)(PRM + 7 * 64 + 8 * q + 4 * hi);
; #pragma unroll
;             for (int p = 0; p < 4; ++p) { const int rb = q >> 2, r = (q & 3) * 4 + p;
;                 const float rr = pg8::sigm(ar[rb][r] + br[p]), ii = pg8::sigm(ai_[rb][r] + bi[p]);
;                 const float a0 = __builtin_amdgcn_exp2f(cf[p] * rr);
;                 av[q][p] = a0; uv[q][p] = __builtin_amdgcn_sqrtf(fmaxf(1.f - a0 * a0, 0.f)) * (ii * xc[q][p]); }
;     ...
;     if (PASS == 1) {
; #pragma unroll
;     for (int q = 0; q < 8; ++q)
;         asm volatile("s_nop 1\n\t"
;             LRU_STEP("row_shr:1 row_mask:0xf bank_mask:0xf") LRU_STEP("row_shr:2 row_mask:0xf bank_mask:0xf") LRU_STEP("row_shr:4 row_mask:0xf bank_mask:0xf")
;             LRU_STEP("row_shr:8 row_mask:0xf bank_mask:0xf") LRU_STEP("row_bcast:15 row_mask:0xa bank_mask:0xf")
;             : "+v"(uv[q][0]), "+v"(av[q][0]), "+v"(uv[q][1]), "+v"(av[q][1]), "+v"(uv[q][2]), "+v"(av[q][2]), "+v"(uv[q][3]), "+v"(av[q][3]));
	v_mul_f32_e32 v14, v112, v14
	v_add_f32_e32 v15, v15, v97
	v_sqrt_f32_e32 v13, v13
	v_exp_f32_e32 v27, v26
	v_exp_f32_e32 v26, v14
	v_mul_f32_e32 v15, 0xbfb8aa3b, v15
	v_exp_f32_e32 v15, v15
	v_mul_f32_e32 v0, v82, v0
	v_mul_f32_e32 v13, v0, v13
	v_add_f32_e32 v0, 1.0, v27
	v_fma_f32 v14, -v26, v26, 1.0
	v_rcp_f32_e32 v0, v0
	v_max_f32_e32 v14, 0, v14
	v_add_f32_e32 v27, v31, v109
	v_add_f32_e32 v15, 1.0, v15
	v_sqrt_f32_e32 v14, v14
	v_mul_f32_e32 v27, 0xbfb8aa3b, v27
	v_rcp_f32_e32 v15, v15
	v_exp_f32_e32 v28, v27
	v_mul_f32_e32 v0, v77, v0
	v_mul_f32_e32 v27, v0, v14
	v_mul_f32_e32 v14, v113, v15
	v_add_f32_e32 v0, 1.0, v28
	v_exp_f32_e32 v28, v14
	v_add_f32_e32 v14, v16, v98
	v_mul_f32_e32 v14, 0xbfb8aa3b, v14
	v_rcp_f32_e32 v0, v0
	v_fma_f32 v15, -v28, v28, 1.0
	v_exp_f32_e32 v14, v14
	v_max_f32_e32 v15, 0, v15
	v_sqrt_f32_e32 v15, v15
	v_mul_f32_e32 v0, v76, v0
	v_add_f32_e32 v14, 1.0, v14
	v_rcp_f32_e32 v14, v14
	v_mul_f32_e32 v29, v0, v15
	v_add_f32_e32 v15, v17, v99
	v_mul_f32_e32 v15, 0xbfb8aa3b, v15
	v_exp_f32_e32 v15, v15
	v_add_f32_e32 v16, v32, v110
	v_mul_f32_e32 v16, 0xbfb8aa3b, v16
	v_mul_f32_e32 v14, v114, v14
	v_exp_f32_e32 v16, v16
	v_exp_f32_e32 v14, v14
	v_add_f32_e32 v15, 1.0, v15
	v_rcp_f32_e32 v15, v15
	v_add_f32_e32 v0, 1.0, v16
	v_fma_f32 v16, -v14, v14, 1.0
	v_max_f32_e32 v17, 0, v16
	v_add_f32_e32 v16, v33, v111
	v_mul_f32_e32 v16, 0xbfb8aa3b, v16
	v_mul_f32_e32 v15, v115, v15
	v_exp_f32_e32 v30, v16
	v_exp_f32_e32 v16, v15
	v_rcp_f32_e32 v0, v0
	v_sqrt_f32_e32 v15, v17
	v_add_f32_e32 v17, 1.0, v30
	v_fma_f32 v30, -v16, v16, 1.0
	v_rcp_f32_e32 v17, v17
	v_max_f32_e32 v30, 0, v30
	v_sqrt_f32_e32 v30, v30
	v_mul_f32_e32 v0, v74, v0
	s_mov_b64 s[4:5], 0x29c00000
	v_mul_f32_e32 v15, v0, v15
	v_mul_f32_e32 v0, v75, v17
	v_lshl_add_u64 v[70:71], v[72:73], 0, s[4:5]
	v_mul_f32_e32 v17, v0, v30
	v_add_co_u32_e32 v72, vcc, s2, v72
	s_nop 1
	v_fmac_f32_dpp v67, v67, v66 row_shr:1 row_mask:0xf bank_mask:0xf
	v_fmac_f32_dpp v69, v69, v68 row_shr:1 row_mask:0xf bank_mask:0xf
	v_fmac_f32_dpp v35, v35, v34 row_shr:1 row_mask:0xf bank_mask:0xf
	v_fmac_f32_dpp v37, v37, v36 row_shr:1 row_mask:0xf bank_mask:0xf
	v_mul_f32_dpp v66, v66, v66 row_shr:1 row_mask:0xf bank_mask:0xf
	v_mul_f32_dpp v68, v68, v68 row_shr:1 row_mask:0xf bank_mask:0xf
	v_mul_f32_dpp v34, v34, v34 row_shr:1 row_mask:0xf bank_mask:0xf
	v_mul_f32_dpp v36, v36, v36 row_shr:1 row_mask:0xf bank_mask:0xf
	v_fmac_f32_dpp v67, v67, v66 row_shr:2 row_mask:0xf bank_mask:0xf
	v_fmac_f32_dpp v69, v69, v68 row_shr:2 row_mask:0xf bank_mask:0xf
	v_fmac_f32_dpp v35, v35, v34 row_shr:2 row_mask:0xf bank_mask:0xf
	v_fmac_f32_dpp v37, v37, v36 row_shr:2 row_mask:0xf bank_mask:0xf
	v_mul_f32_dpp v66, v66, v66 row_shr:2 row_mask:0xf bank_mask:0xf
	v_mul_f32_dpp v68, v68, v68 row_shr:2 row_mask:0xf bank_mask:0xf
	v_mul_f32_dpp v34, v34, v34 row_shr:2 row_mask:0xf bank_mask:0xf
	v_mul_f32_dpp v36, v36, v36 row_shr:2 row_mask:0xf bank_mask:0xf
	v_fmac_f32_dpp v67, v67, v66 row_shr:4 row_mask:0xf bank_mask:0xf
	v_fmac_f32_dpp v69, v69, v68 row_shr:4 row_mask:0xf bank_mask:0xf
	v_fmac_f32_dpp v35, v35, v34 row_shr:4 row_mask:0xf bank_mask:0xf
	v_fmac_f32_dpp v37, v37, v36 row_shr:4 row_mask:0xf bank_mask:0xf
	v_mul_f32_dpp v66, v66, v66 row_shr:4 row_mask:0xf bank_mask:0xf
	v_mul_f32_dpp v68, v68, v68 row_shr:4 row_mask:0xf bank_mask:0xf
	v_mul_f32_dpp v34, v34, v34 row_shr:4 row_mask:0xf bank_mask:0xf
	v_mul_f32_dpp v36, v36, v36 row_shr:4 row_mask:0xf bank_mask:0xf
	v_fmac_f32_dpp v67, v67, v66 row_shr:8 row_mask:0xf bank_mask:0xf
	v_fmac_f32_dpp v69, v69, v68 row_shr:8 row_mask:0xf bank_mask:0xf
	v_fmac_f32_dpp v35, v35, v34 row_shr:8 row_mask:0xf bank_mask:0xf
	v_fmac_f32_dpp v37, v37, v36 row_shr:8 row_mask:0xf bank_mask:0xf
	v_mul_f32_dpp v66, v66, v66 row_shr:8 row_mask:0xf bank_mask:0xf
	v_mul_f32_dpp v68, v68, v68 row_shr:8 row_mask:0xf bank_mask:0xf
	v_mul_f32_dpp v34, v34, v34 row_shr:8 row_mask:0xf bank_mask:0xf
	v_mul_f32_dpp v36, v36, v36 row_shr:8 row_mask:0xf bank_mask:0xf
	v_fmac_f32_dpp v67, v67, v66 row_bcast:15 row_mask:0xa bank_mask:0xf
	v_fmac_f32_dpp v69, v69, v68 row_bcast:15 row_mask:0xa bank_mask:0xf
	v_fmac_f32_dpp v35, v35, v34 row_bcast:15 row_mask:0xa bank_mask:0xf
	v_fmac_f32_dpp v37, v37, v36 row_bcast:15 row_mask:0xa bank_mask:0xf
	v_mul_f32_dpp v66, v66, v66 row_bcast:15 row_mask:0xa bank_mask:0xf
	v_mul_f32_dpp v68, v68, v68 row_bcast:15 row_mask:0xa bank_mask:0xf
	v_mul_f32_dpp v34, v34, v34 row_bcast:15 row_mask:0xa bank_mask:0xf
	v_mul_f32_dpp v36, v36, v36 row_bcast:15 row_mask:0xa bank_mask:0xf

; template <int PASS>
; __device__ __forceinline__ void lru_unit(const LruPtrs& args, LAS unsigned char* lds, int chunk, int bl, int g, int ck) {
;     ...
;     if (PASS == 1) {
; #pragma unroll
;     for (int q = 0; q < 8; ++q)
;         asm volatile("s_nop 1\n\t"
;             LRU_STEP("row_shr:1 row_mask:0xf bank_mask:0xf") LRU_STEP("row_shr:2 row_mask:0xf bank_mask:0xf") LRU_STEP("row_shr:4 row_mask:0xf bank_mask:0xf")
;             LRU_STEP("row_shr:8 row_mask:0xf bank_mask:0xf") LRU_STEP("row_bcast:15 row_mask:0xa bank_mask:0xf")
;             : "+v"(uv[q][0]), "+v"(av[q][0]), "+v"(uv[q][1]), "+v"(av[q][1]), "+v"(uv[q][2]), "+v"(av[q][2]), "+v"(uv[q][3]), "+v"(av[q][3]));
	s_nop 1
	v_fmac_f32_dpp v51, v51, v50 row_shr:1 row_mask:0xf bank_mask:0xf
	v_fmac_f32_dpp v53, v53, v52 row_shr:1 row_mask:0xf bank_mask:0xf
	v_fmac_f32_dpp v39, v39, v38 row_shr:1 row_mask:0xf bank_mask:0xf
	v_fmac_f32_dpp v41, v41, v40 row_shr:1 row_mask:0xf bank_mask:0xf
	v_mul_f32_dpp v50, v50, v50 row_shr:1 row_mask:0xf bank_mask:0xf
	v_mul_f32_dpp v52, v52, v52 row_shr:1 row_mask:0xf bank_mask:0xf
	v_mul_f32_dpp v38, v38, v38 row_shr:1 row_mask:0xf bank_mask:0xf
	v_mul_f32_dpp v40, v40, v40 row_shr:1 row_mask:0xf bank_mask:0xf
	v_fmac_f32_dpp v51, v51, v50 row_shr:2 row_mask:0xf bank_mask:0xf
	v_fmac_f32_dpp v53, v53, v52 row_shr:2 row_mask:0xf bank_mask:0xf
	v_fmac_f32_dpp v39, v39, v38 row_shr:2 row_mask:0xf bank_mask:0xf
	v_fmac_f32_dpp v41, v41, v40 row_shr:2 row_mask:0xf bank_mask:0xf
	v_mul_f32_dpp v50, v50, v50 row_shr:2 row_mask:0xf bank_mask:0xf
	v_mul_f32_dpp v52, v52, v52 row_shr:2 row_mask:0xf bank_mask:0xf
	v_mul_f32_dpp v38, v38, v38 row_shr:2 row_mask:0xf bank_mask:0xf
	v_mul_f32_dpp v40, v40, v40 row_shr:2 row_mask:0xf bank_mask:0xf
	v_fmac_f32_dpp v51, v51, v50 row_shr:4 row_mask:0xf bank_mask:0xf
	v_fmac_f32_dpp v53, v53, v52 row_shr:4 row_mask:0xf bank_mask:0xf
	v_fmac_f32_dpp v39, v39, v38 row_shr:4 row_mask:0xf bank_mask:0xf
	v_fmac_f32_dpp v41, v41, v40 row_shr:4 row_mask:0xf bank_mask:0xf
	v_mul_f32_dpp v50, v50, v50 row_shr:4 row_mask:0xf bank_mask:0xf
	v_mul_f32_dpp v52, v52, v52 row_shr:4 row_mask:0xf bank_mask:0xf
	v_mul_f32_dpp v38, v38, v38 row_shr:4 row_mask:0xf bank_mask:0xf
	v_mul_f32_dpp v40, v40, v40 row_shr:4 row_mask:0xf bank_mask:0xf
	v_fmac_f32_dpp v51, v51, v50 row_shr:8 row_mask:0xf bank_mask:0xf
	v_fmac_f32_dpp v53, v53, v52 row_shr:8 row_mask:0xf bank_mask:0xf
	v_fmac_f32_dpp v39, v39, v38 row_shr:8 row_mask:0xf bank_mask:0xf
	v_fmac_f32_dpp v41, v41, v40 row_shr:8 row_mask:0xf bank_mask:0xf
	v_mul_f32_dpp v50, v50, v50 row_shr:8 row_mask:0xf bank_mask:0xf
	v_mul_f32_dpp v52, v52, v52 row_shr:8 row_mask:0xf bank_mask:0xf
	v_mul_f32_dpp v38, v38, v38 row_shr:8 row_mask:0xf bank_mask:0xf
	v_mul_f32_dpp v40, v40, v40 row_shr:8 row_mask:0xf bank_mask:0xf
	v_fmac_f32_dpp v51, v51, v50 row_bcast:15 row_mask:0xa bank_mask:0xf
	v_fmac_f32_dpp v53, v53, v52 row_bcast:15 row_mask:0xa bank_mask:0xf
	v_fmac_f32_dpp v39, v39, v38 row_bcast:15 row_mask:0xa bank_mask:0xf
	v_fmac_f32_dpp v41, v41, v40 row_bcast:15 row_mask:0xa bank_mask:0xf
	v_mul_f32_dpp v50, v50, v50 row_bcast:15 row_mask:0xa bank_mask:0xf
	v_mul_f32_dpp v52, v52, v52 row_bcast:15 row_mask:0xa bank_mask:0xf
	v_mul_f32_dpp v38, v38, v38 row_bcast:15 row_mask:0xa bank_mask:0xf
	v_mul_f32_dpp v40, v40, v40 row_bcast:15 row_mask:0xa bank_mask:0xf

; template <int PASS>
; __device__ __forceinline__ void lru_unit(const LruPtrs& args, LAS unsigned char* lds, int chunk, int bl, int g, int ck) {
;     ...
;     if (PASS == 1) {
; #pragma unroll
;     for (int q = 0; q < 8; ++q)
;         asm volatile("s_nop 1\n\t"
;             LRU_STEP("row_shr:1 row_mask:0xf bank_mask:0xf") LRU_STEP("row_shr:2 row_mask:0xf bank_mask:0xf") LRU_STEP("row_shr:4 row_mask:0xf bank_mask:0xf")
;             LRU_STEP("row_shr:8 row_mask:0xf bank_mask:0xf") LRU_STEP("row_bcast:15 row_mask:0xa bank_mask:0xf")
;             : "+v"(uv[q][0]), "+v"(av[q][0]), "+v"(uv[q][1]), "+v"(av[q][1]), "+v"(uv[q][2]), "+v"(av[q][2]), "+v"(uv[q][3]), "+v"(av[q][3]));
	s_nop 1
	v_fmac_f32_dpp v55, v55, v54 row_shr:1 row_mask:0xf bank_mask:0xf
	v_fmac_f32_dpp v57, v57, v56 row_shr:1 row_mask:0xf bank_mask:0xf
	v_fmac_f32_dpp v43, v43, v42 row_shr:1 row_mask:0xf bank_mask:0xf
	v_fmac_f32_dpp v45, v45, v44 row_shr:1 row_mask:0xf bank_mask:0xf
	v_mul_f32_dpp v54, v54, v54 row_shr:1 row_mask:0xf bank_mask:0xf
	v_mul_f32_dpp v56, v56, v56 row_shr:1 row_mask:0xf bank_mask:0xf
	v_mul_f32_dpp v42, v42, v42 row_shr:1 row_mask:0xf bank_mask:0xf
	v_mul_f32_dpp v44, v44, v44 row_shr:1 row_mask:0xf bank_mask:0xf
	v_fmac_f32_dpp v55, v55, v54 row_shr:2 row_mask:0xf bank_mask:0xf
	v_fmac_f32_dpp v57, v57, v56 row_shr:2 row_mask:0xf bank_mask:0xf
	v_fmac_f32_dpp v43, v43, v42 row_shr:2 row_mask:0xf bank_mask:0xf
	v_fmac_f32_dpp v45, v45, v44 row_shr:2 row_mask:0xf bank_mask:0xf
	v_mul_f32_dpp v54, v54, v54 row_shr:2 row_mask:0xf bank_mask:0xf
	v_mul_f32_dpp v56, v56, v56 row_shr:2 row_mask:0xf bank_mask:0xf
	v_mul_f32_dpp v42, v42, v42 row_shr:2 row_mask:0xf bank_mask:0xf
	v_mul_f32_dpp v44, v44, v44 row_shr:2 row_mask:0xf bank_mask:0xf
	v_fmac_f32_dpp v55, v55, v54 row_shr:4 row_mask:0xf bank_mask:0xf
	v_fmac_f32_dpp v57, v57, v56 row_shr:4 row_mask:0xf bank_mask:0xf
	v_fmac_f32_dpp v43, v43, v42 row_shr:4 row_mask:0xf bank_mask:0xf
	v_fmac_f32_dpp v45, v45, v44 row_shr:4 row_mask:0xf bank_mask:0xf
	v_mul_f32_dpp v54, v54, v54 row_shr:4 row_mask:0xf bank_mask:0xf
	v_mul_f32_dpp v56, v56, v56 row_shr:4 row_mask:0xf bank_mask:0xf
	v_mul_f32_dpp v42, v42, v42 row_shr:4 row_mask:0xf bank_mask:0xf
	v_mul_f32_dpp v44, v44, v44 row_shr:4 row_mask:0xf bank_mask:0xf
	v_fmac_f32_dpp v55, v55, v54 row_shr:8 row_mask:0xf bank_mask:0xf
	v_fmac_f32_dpp v57, v57, v56 row_shr:8 row_mask:0xf bank_mask:0xf
	v_fmac_f32_dpp v43, v43, v42 row_shr:8 row_mask:0xf bank_mask:0xf
	v_fmac_f32_dpp v45, v45, v44 row_shr:8 row_mask:0xf bank_mask:0xf
	v_mul_f32_dpp v54, v54, v54 row_shr:8 row_mask:0xf bank_mask:0xf
	v_mul_f32_dpp v56, v56, v56 row_shr:8 row_mask:0xf bank_mask:0xf
	v_mul_f32_dpp v42, v42, v42 row_shr:8 row_mask:0xf bank_mask:0xf
	v_mul_f32_dpp v44, v44, v44 row_shr:8 row_mask:0xf bank_mask:0xf
	v_fmac_f32_dpp v55, v55, v54 row_bcast:15 row_mask:0xa bank_mask:0xf
	v_fmac_f32_dpp v57, v57, v56 row_bcast:15 row_mask:0xa bank_mask:0xf
	v_fmac_f32_dpp v43, v43, v42 row_bcast:15 row_mask:0xa bank_mask:0xf
	v_fmac_f32_dpp v45, v45, v44 row_bcast:15 row_mask:0xa bank_mask:0xf
	v_mul_f32_dpp v54, v54, v54 row_bcast:15 row_mask:0xa bank_mask:0xf
	v_mul_f32_dpp v56, v56, v56 row_bcast:15 row_mask:0xa bank_mask:0xf
	v_mul_f32_dpp v42, v42, v42 row_bcast:15 row_mask:0xa bank_mask:0xf
	v_mul_f32_dpp v44, v44, v44 row_bcast:15 row_mask:0xa bank_mask:0xf

; template <int PASS>
; __device__ __forceinline__ void lru_unit(const LruPtrs& args, LAS unsigned char* lds, int chunk, int bl, int g, int ck) {
;     ...
;     if (PASS == 1) {
; #pragma unroll
;     for (int q = 0; q < 8; ++q)
;         asm volatile("s_nop 1\n\t"
;             LRU_STEP("row_shr:1 row_mask:0xf bank_mask:0xf") LRU_STEP("row_shr:2 row_mask:0xf bank_mask:0xf") LRU_STEP("row_shr:4 row_mask:0xf bank_mask:0xf")
;             LRU_STEP("row_shr:8 row_mask:0xf bank_mask:0xf") LRU_STEP("row_bcast:15 row_mask:0xa bank_mask:0xf")
;             : "+v"(uv[q][0]), "+v"(av[q][0]), "+v"(uv[q][1]), "+v"(av[q][1]), "+v"(uv[q][2]), "+v"(av[q][2]), "+v"(uv[q][3]), "+v"(av[q][3]));
	s_nop 1
	v_fmac_f32_dpp v59, v59, v58 row_shr:1 row_mask:0xf bank_mask:0xf
	v_fmac_f32_dpp v61, v61, v60 row_shr:1 row_mask:0xf bank_mask:0xf
	v_fmac_f32_dpp v47, v47, v46 row_shr:1 row_mask:0xf bank_mask:0xf
	v_fmac_f32_dpp v49, v49, v48 row_shr:1 row_mask:0xf bank_mask:0xf
	v_mul_f32_dpp v58, v58, v58 row_shr:1 row_mask:0xf bank_mask:0xf
	v_mul_f32_dpp v60, v60, v60 row_shr:1 row_mask:0xf bank_mask:0xf
	v_mul_f32_dpp v46, v46, v46 row_shr:1 row_mask:0xf bank_mask:0xf
	v_mul_f32_dpp v48, v48, v48 row_shr:1 row_mask:0xf bank_mask:0xf
	v_fmac_f32_dpp v59, v59, v58 row_shr:2 row_mask:0xf bank_mask:0xf
	v_fmac_f32_dpp v61, v61, v60 row_shr:2 row_mask:0xf bank_mask:0xf
	v_fmac_f32_dpp v47, v47, v46 row_shr:2 row_mask:0xf bank_mask:0xf
	v_fmac_f32_dpp v49, v49, v48 row_shr:2 row_mask:0xf bank_mask:0xf
	v_mul_f32_dpp v58, v58, v58 row_shr:2 row_mask:0xf bank_mask:0xf
	v_mul_f32_dpp v60, v60, v60 row_shr:2 row_mask:0xf bank_mask:0xf
	v_mul_f32_dpp v46, v46, v46 row_shr:2 row_mask:0xf bank_mask:0xf
	v_mul_f32_dpp v48, v48, v48 row_shr:2 row_mask:0xf bank_mask:0xf
	v_fmac_f32_dpp v59, v59, v58 row_shr:4 row_mask:0xf bank_mask:0xf
	v_fmac_f32_dpp v61, v61, v60 row_shr:4 row_mask:0xf bank_mask:0xf
	v_fmac_f32_dpp v47, v47, v46 row_shr:4 row_mask:0xf bank_mask:0xf
	v_fmac_f32_dpp v49, v49, v48 row_shr:4 row_mask:0xf bank_mask:0xf
	v_mul_f32_dpp v58, v58, v58 row_shr:4 row_mask:0xf bank_mask:0xf
	v_mul_f32_dpp v60, v60, v60 row_shr:4 row_mask:0xf bank_mask:0xf
	v_mul_f32_dpp v46, v46, v46 row_shr:4 row_mask:0xf bank_mask:0xf
	v_mul_f32_dpp v48, v48, v48 row_shr:4 row_mask:0xf bank_mask:0xf
	v_fmac_f32_dpp v59, v59, v58 row_shr:8 row_mask:0xf bank_mask:0xf
	v_fmac_f32_dpp v61, v61, v60 row_shr:8 row_mask:0xf bank_mask:0xf
	v_fmac_f32_dpp v47, v47, v46 row_shr:8 row_mask:0xf bank_mask:0xf
	v_fmac_f32_dpp v49, v49, v48 row_shr:8 row_mask:0xf bank_mask:0xf
	v_mul_f32_dpp v58, v58, v58 row_shr:8 row_mask:0xf bank_mask:0xf
	v_mul_f32_dpp v60, v60, v60 row_shr:8 row_mask:0xf bank_mask:0xf
	v_mul_f32_dpp v46, v46, v46 row_shr:8 row_mask:0xf bank_mask:0xf
	v_mul_f32_dpp v48, v48, v48 row_shr:8 row_mask:0xf bank_mask:0xf
	v_fmac_f32_dpp v59, v59, v58 row_bcast:15 row_mask:0xa bank_mask:0xf
	v_fmac_f32_dpp v61, v61, v60 row_bcast:15 row_mask:0xa bank_mask:0xf
	v_fmac_f32_dpp v47, v47, v46 row_bcast:15 row_mask:0xa bank_mask:0xf
	v_fmac_f32_dpp v49, v49, v48 row_bcast:15 row_mask:0xa bank_mask:0xf
	v_mul_f32_dpp v58, v58, v58 row_bcast:15 row_mask:0xa bank_mask:0xf
	v_mul_f32_dpp v60, v60, v60 row_bcast:15 row_mask:0xa bank_mask:0xf
	v_mul_f32_dpp v46, v46, v46 row_bcast:15 row_mask:0xa bank_mask:0xf
	v_mul_f32_dpp v48, v48, v48 row_bcast:15 row_mask:0xa bank_mask:0xf

; template <int PASS>
; __device__ __forceinline__ void lru_unit(const LruPtrs& args, LAS unsigned char* lds, int chunk, int bl, int g, int ck) {
;     ...
;     if (PASS == 1) {
; #pragma unroll
;     for (int q = 0; q < 8; ++q)
;         asm volatile("s_nop 1\n\t"
;             LRU_STEP("row_shr:1 row_mask:0xf bank_mask:0xf") LRU_STEP("row_shr:2 row_mask:0xf bank_mask:0xf") LRU_STEP("row_shr:4 row_mask:0xf bank_mask:0xf")
;             LRU_STEP("row_shr:8 row_mask:0xf bank_mask:0xf") LRU_STEP("row_bcast:15 row_mask:0xa bank_mask:0xf")
;             : "+v"(uv[q][0]), "+v"(av[q][0]), "+v"(uv[q][1]), "+v"(av[q][1]), "+v"(uv[q][2]), "+v"(av[q][2]), "+v"(uv[q][3]), "+v"(av[q][3]));
	s_nop 1
	v_fmac_f32_dpp v63, v63, v62 row_shr:1 row_mask:0xf bank_mask:0xf
	v_fmac_f32_dpp v65, v65, v64 row_shr:1 row_mask:0xf bank_mask:0xf
	v_fmac_f32_dpp v3, v3, v2 row_shr:1 row_mask:0xf bank_mask:0xf
	v_fmac_f32_dpp v5, v5, v4 row_shr:1 row_mask:0xf bank_mask:0xf
	v_mul_f32_dpp v62, v62, v62 row_shr:1 row_mask:0xf bank_mask:0xf
	v_mul_f32_dpp v64, v64, v64 row_shr:1 row_mask:0xf bank_mask:0xf
	v_mul_f32_dpp v2, v2, v2 row_shr:1 row_mask:0xf bank_mask:0xf
	v_mul_f32_dpp v4, v4, v4 row_shr:1 row_mask:0xf bank_mask:0xf
	v_fmac_f32_dpp v63, v63, v62 row_shr:2 row_mask:0xf bank_mask:0xf
	v_fmac_f32_dpp v65, v65, v64 row_shr:2 row_mask:0xf bank_mask:0xf
	v_fmac_f32_dpp v3, v3, v2 row_shr:2 row_mask:0xf bank_mask:0xf
	v_fmac_f32_dpp v5, v5, v4 row_shr:2 row_mask:0xf bank_mask:0xf
	v_mul_f32_dpp v62, v62, v62 row_shr:2 row_mask:0xf bank_mask:0xf
	v_mul_f32_dpp v64, v64, v64 row_shr:2 row_mask:0xf bank_mask:0xf
	v_mul_f32_dpp v2, v2, v2 row_shr:2 row_mask:0xf bank_mask:0xf
	v_mul_f32_dpp v4, v4, v4 row_shr:2 row_mask:0xf bank_mask:0xf
	v_fmac_f32_dpp v63, v63, v62 row_shr:4 row_mask:0xf bank_mask:0xf
	v_fmac_f32_dpp v65, v65, v64 row_shr:4 row_mask:0xf bank_mask:0xf
	v_fmac_f32_dpp v3, v3, v2 row_shr:4 row_mask:0xf bank_mask:0xf
	v_fmac_f32_dpp v5, v5, v4 row_shr:4 row_mask:0xf bank_mask:0xf
	v_mul_f32_dpp v62, v62, v62 row_shr:4 row_mask:0xf bank_mask:0xf
	v_mul_f32_dpp v64, v64, v64 row_shr:4 row_mask:0xf bank_mask:0xf
	v_mul_f32_dpp v2, v2, v2 row_shr:4 row_mask:0xf bank_mask:0xf
	v_mul_f32_dpp v4, v4, v4 row_shr:4 row_mask:0xf bank_mask:0xf
	v_fmac_f32_dpp v63, v63, v62 row_shr:8 row_mask:0xf bank_mask:0xf
	v_fmac_f32_dpp v65, v65, v64 row_shr:8 row_mask:0xf bank_mask:0xf
	v_fmac_f32_dpp v3, v3, v2 row_shr:8 row_mask:0xf bank_mask:0xf
	v_fmac_f32_dpp v5, v5, v4 row_shr:8 row_mask:0xf bank_mask:0xf
	v_mul_f32_dpp v62, v62, v62 row_shr:8 row_mask:0xf bank_mask:0xf
	v_mul_f32_dpp v64, v64, v64 row_shr:8 row_mask:0xf bank_mask:0xf
	v_mul_f32_dpp v2, v2, v2 row_shr:8 row_mask:0xf bank_mask:0xf
	v_mul_f32_dpp v4, v4, v4 row_shr:8 row_mask:0xf bank_mask:0xf
	v_fmac_f32_dpp v63, v63, v62 row_bcast:15 row_mask:0xa bank_mask:0xf
	v_fmac_f32_dpp v65, v65, v64 row_bcast:15 row_mask:0xa bank_mask:0xf
	v_fmac_f32_dpp v3, v3, v2 row_bcast:15 row_mask:0xa bank_mask:0xf
	v_fmac_f32_dpp v5, v5, v4 row_bcast:15 row_mask:0xa bank_mask:0xf
	v_mul_f32_dpp v62, v62, v62 row_bcast:15 row_mask:0xa bank_mask:0xf
	v_mul_f32_dpp v64, v64, v64 row_bcast:15 row_mask:0xa bank_mask:0xf
	v_mul_f32_dpp v2, v2, v2 row_bcast:15 row_mask:0xa bank_mask:0xf
	v_mul_f32_dpp v4, v4, v4 row_bcast:15 row_mask:0xa bank_mask:0xf

; template <int PASS>
; __device__ __forceinline__ void lru_unit(const LruPtrs& args, LAS unsigned char* lds, int chunk, int bl, int g, int ck) {
;     ...
;     if (PASS == 1) {
; #pragma unroll
;     for (int q = 0; q < 8; ++q)
;         asm volatile("s_nop 1\n\t"
;             LRU_STEP("row_shr:1 row_mask:0xf bank_mask:0xf") LRU_STEP("row_shr:2 row_mask:0xf bank_mask:0xf") LRU_STEP("row_shr:4 row_mask:0xf bank_mask:0xf")
;             LRU_STEP("row_shr:8 row_mask:0xf bank_mask:0xf") LRU_STEP("row_bcast:15 row_mask:0xa bank_mask:0xf")
;             : "+v"(uv[q][0]), "+v"(av[q][0]), "+v"(uv[q][1]), "+v"(av[q][1]), "+v"(uv[q][2]), "+v"(av[q][2]), "+v"(uv[q][3]), "+v"(av[q][3]));
	s_nop 1
	v_fmac_f32_dpp v19, v19, v18 row_shr:1 row_mask:0xf bank_mask:0xf
	v_fmac_f32_dpp v21, v21, v20 row_shr:1 row_mask:0xf bank_mask:0xf
	v_fmac_f32_dpp v7, v7, v6 row_shr:1 row_mask:0xf bank_mask:0xf
	v_fmac_f32_dpp v9, v9, v8 row_shr:1 row_mask:0xf bank_mask:0xf
	v_mul_f32_dpp v18, v18, v18 row_shr:1 row_mask:0xf bank_mask:0xf
	v_mul_f32_dpp v20, v20, v20 row_shr:1 row_mask:0xf bank_mask:0xf
	v_mul_f32_dpp v6, v6, v6 row_shr:1 row_mask:0xf bank_mask:0xf
	v_mul_f32_dpp v8, v8, v8 row_shr:1 row_mask:0xf bank_mask:0xf
	v_fmac_f32_dpp v19, v19, v18 row_shr:2 row_mask:0xf bank_mask:0xf
	v_fmac_f32_dpp v21, v21, v20 row_shr:2 row_mask:0xf bank_mask:0xf
	v_fmac_f32_dpp v7, v7, v6 row_shr:2 row_mask:0xf bank_mask:0xf
	v_fmac_f32_dpp v9, v9, v8 row_shr:2 row_mask:0xf bank_mask:0xf
	v_mul_f32_dpp v18, v18, v18 row_shr:2 row_mask:0xf bank_mask:0xf
	v_mul_f32_dpp v20, v20, v20 row_shr:2 row_mask:0xf bank_mask:0xf
	v_mul_f32_dpp v6, v6, v6 row_shr:2 row_mask:0xf bank_mask:0xf
	v_mul_f32_dpp v8, v8, v8 row_shr:2 row_mask:0xf bank_mask:0xf
	v_fmac_f32_dpp v19, v19, v18 row_shr:4 row_mask:0xf bank_mask:0xf
	v_fmac_f32_dpp v21, v21, v20 row_shr:4 row_mask:0xf bank_mask:0xf
	v_fmac_f32_dpp v7, v7, v6 row_shr:4 row_mask:0xf bank_mask:0xf
	v_fmac_f32_dpp v9, v9, v8 row_shr:4 row_mask:0xf bank_mask:0xf
	v_mul_f32_dpp v18, v18, v18 row_shr:4 row_mask:0xf bank_mask:0xf
	v_mul_f32_dpp v20, v20, v20 row_shr:4 row_mask:0xf bank_mask:0xf
	v_mul_f32_dpp v6, v6, v6 row_shr:4 row_mask:0xf bank_mask:0xf
	v_mul_f32_dpp v8, v8, v8 row_shr:4 row_mask:0xf bank_mask:0xf
	v_fmac_f32_dpp v19, v19, v18 row_shr:8 row_mask:0xf bank_mask:0xf
	v_fmac_f32_dpp v21, v21, v20 row_shr:8 row_mask:0xf bank_mask:0xf
	v_fmac_f32_dpp v7, v7, v6 row_shr:8 row_mask:0xf bank_mask:0xf
	v_fmac_f32_dpp v9, v9, v8 row_shr:8 row_mask:0xf bank_mask:0xf
	v_mul_f32_dpp v18, v18, v18 row_shr:8 row_mask:0xf bank_mask:0xf
	v_mul_f32_dpp v20, v20, v20 row_shr:8 row_mask:0xf bank_mask:0xf
	v_mul_f32_dpp v6, v6, v6 row_shr:8 row_mask:0xf bank_mask:0xf
	v_mul_f32_dpp v8, v8, v8 row_shr:8 row_mask:0xf bank_mask:0xf
	v_fmac_f32_dpp v19, v19, v18 row_bcast:15 row_mask:0xa bank_mask:0xf
	v_fmac_f32_dpp v21, v21, v20 row_bcast:15 row_mask:0xa bank_mask:0xf
	v_fmac_f32_dpp v7, v7, v6 row_bcast:15 row_mask:0xa bank_mask:0xf
	v_fmac_f32_dpp v9, v9, v8 row_bcast:15 row_mask:0xa bank_mask:0xf
	v_mul_f32_dpp v18, v18, v18 row_bcast:15 row_mask:0xa bank_mask:0xf
	v_mul_f32_dpp v20, v20, v20 row_bcast:15 row_mask:0xa bank_mask:0xf
	v_mul_f32_dpp v6, v6, v6 row_bcast:15 row_mask:0xa bank_mask:0xf
	v_mul_f32_dpp v8, v8, v8 row_bcast:15 row_mask:0xa bank_mask:0xf

; template <int PASS>
; __device__ __forceinline__ void lru_unit(const LruPtrs& args, LAS unsigned char* lds, int chunk, int bl, int g, int ck) {
;     ...
;     if (PASS == 1) {
; #pragma unroll
;     for (int q = 0; q < 8; ++q)
;         asm volatile("s_nop 1\n\t"
;             LRU_STEP("row_shr:1 row_mask:0xf bank_mask:0xf") LRU_STEP("row_shr:2 row_mask:0xf bank_mask:0xf") LRU_STEP("row_shr:4 row_mask:0xf bank_mask:0xf")
;             LRU_STEP("row_shr:8 row_mask:0xf bank_mask:0xf") LRU_STEP("row_bcast:15 row_mask:0xa bank_mask:0xf")
;             : "+v"(uv[q][0]), "+v"(av[q][0]), "+v"(uv[q][1]), "+v"(av[q][1]), "+v"(uv[q][2]), "+v"(av[q][2]), "+v"(uv[q][3]), "+v"(av[q][3]));
	s_nop 1
	v_fmac_f32_dpp v23, v23, v22 row_shr:1 row_mask:0xf bank_mask:0xf
	v_fmac_f32_dpp v25, v25, v24 row_shr:1 row_mask:0xf bank_mask:0xf
	v_fmac_f32_dpp v11, v11, v10 row_shr:1 row_mask:0xf bank_mask:0xf
	v_fmac_f32_dpp v13, v13, v12 row_shr:1 row_mask:0xf bank_mask:0xf
	v_mul_f32_dpp v22, v22, v22 row_shr:1 row_mask:0xf bank_mask:0xf
	v_mul_f32_dpp v24, v24, v24 row_shr:1 row_mask:0xf bank_mask:0xf
	v_mul_f32_dpp v10, v10, v10 row_shr:1 row_mask:0xf bank_mask:0xf
	v_mul_f32_dpp v12, v12, v12 row_shr:1 row_mask:0xf bank_mask:0xf
	v_fmac_f32_dpp v23, v23, v22 row_shr:2 row_mask:0xf bank_mask:0xf
	v_fmac_f32_dpp v25, v25, v24 row_shr:2 row_mask:0xf bank_mask:0xf
	v_fmac_f32_dpp v11, v11, v10 row_shr:2 row_mask:0xf bank_mask:0xf
	v_fmac_f32_dpp v13, v13, v12 row_shr:2 row_mask:0xf bank_mask:0xf
	v_mul_f32_dpp v22, v22, v22 row_shr:2 row_mask:0xf bank_mask:0xf
	v_mul_f32_dpp v24, v24, v24 row_shr:2 row_mask:0xf bank_mask:0xf
	v_mul_f32_dpp v10, v10, v10 row_shr:2 row_mask:0xf bank_mask:0xf
	v_mul_f32_dpp v12, v12, v12 row_shr:2 row_mask:0xf bank_mask:0xf
	v_fmac_f32_dpp v23, v23, v22 row_shr:4 row_mask:0xf bank_mask:0xf
	v_fmac_f32_dpp v25, v25, v24 row_shr:4 row_mask:0xf bank_mask:0xf
	v_fmac_f32_dpp v11, v11, v10 row_shr:4 row_mask:0xf bank_mask:0xf
	v_fmac_f32_dpp v13, v13, v12 row_shr:4 row_mask:0xf bank_mask:0xf
	v_mul_f32_dpp v22, v22, v22 row_shr:4 row_mask:0xf bank_mask:0xf
	v_mul_f32_dpp v24, v24, v24 row_shr:4 row_mask:0xf bank_mask:0xf
	v_mul_f32_dpp v10, v10, v10 row_shr:4 row_mask:0xf bank_mask:0xf
	v_mul_f32_dpp v12, v12, v12 row_shr:4 row_mask:0xf bank_mask:0xf
	v_fmac_f32_dpp v23, v23, v22 row_shr:8 row_mask:0xf bank_mask:0xf
	v_fmac_f32_dpp v25, v25, v24 row_shr:8 row_mask:0xf bank_mask:0xf
	v_fmac_f32_dpp v11, v11, v10 row_shr:8 row_mask:0xf bank_mask:0xf
	v_fmac_f32_dpp v13, v13, v12 row_shr:8 row_mask:0xf bank_mask:0xf
	v_mul_f32_dpp v22, v22, v22 row_shr:8 row_mask:0xf bank_mask:0xf
	v_mul_f32_dpp v24, v24, v24 row_shr:8 row_mask:0xf bank_mask:0xf
	v_mul_f32_dpp v10, v10, v10 row_shr:8 row_mask:0xf bank_mask:0xf
	v_mul_f32_dpp v12, v12, v12 row_shr:8 row_mask:0xf bank_mask:0xf
	v_fmac_f32_dpp v23, v23, v22 row_bcast:15 row_mask:0xa bank_mask:0xf
	v_fmac_f32_dpp v25, v25, v24 row_bcast:15 row_mask:0xa bank_mask:0xf
	v_fmac_f32_dpp v11, v11, v10 row_bcast:15 row_mask:0xa bank_mask:0xf
	v_fmac_f32_dpp v13, v13, v12 row_bcast:15 row_mask:0xa bank_mask:0xf
	v_mul_f32_dpp v22, v22, v22 row_bcast:15 row_mask:0xa bank_mask:0xf
	v_mul_f32_dpp v24, v24, v24 row_bcast:15 row_mask:0xa bank_mask:0xf
	v_mul_f32_dpp v10, v10, v10 row_bcast:15 row_mask:0xa bank_mask:0xf
	v_mul_f32_dpp v12, v12, v12 row_bcast:15 row_mask:0xa bank_mask:0xf

; template <int PASS>
; __device__ __forceinline__ void lru_unit(const LruPtrs& args, LAS unsigned char* lds, int chunk, int bl, int g, int ck) {
;     ...
;     if (PASS == 1) {
; #pragma unroll
;     for (int q = 0; q < 8; ++q)
;         asm volatile("s_nop 1\n\t"
;             LRU_STEP("row_shr:1 row_mask:0xf bank_mask:0xf") LRU_STEP("row_shr:2 row_mask:0xf bank_mask:0xf") LRU_STEP("row_shr:4 row_mask:0xf bank_mask:0xf")
;             LRU_STEP("row_shr:8 row_mask:0xf bank_mask:0xf") LRU_STEP("row_bcast:15 row_mask:0xa bank_mask:0xf")
;             : "+v"(uv[q][0]), "+v"(av[q][0]), "+v"(uv[q][1]), "+v"(av[q][1]), "+v"(uv[q][2]), "+v"(av[q][2]), "+v"(uv[q][3]), "+v"(av[q][3]));
	s_nop 1
	v_fmac_f32_dpp v27, v27, v26 row_shr:1 row_mask:0xf bank_mask:0xf
	v_fmac_f32_dpp v29, v29, v28 row_shr:1 row_mask:0xf bank_mask:0xf
	v_fmac_f32_dpp v15, v15, v14 row_shr:1 row_mask:0xf bank_mask:0xf
	v_fmac_f32_dpp v17, v17, v16 row_shr:1 row_mask:0xf bank_mask:0xf
	v_mul_f32_dpp v26, v26, v26 row_shr:1 row_mask:0xf bank_mask:0xf
	v_mul_f32_dpp v28, v28, v28 row_shr:1 row_mask:0xf bank_mask:0xf
	v_mul_f32_dpp v14, v14, v14 row_shr:1 row_mask:0xf bank_mask:0xf
	v_mul_f32_dpp v16, v16, v16 row_shr:1 row_mask:0xf bank_mask:0xf
	v_fmac_f32_dpp v27, v27, v26 row_shr:2 row_mask:0xf bank_mask:0xf
	v_fmac_f32_dpp v29, v29, v28 row_shr:2 row_mask:0xf bank_mask:0xf
	v_fmac_f32_dpp v15, v15, v14 row_shr:2 row_mask:0xf bank_mask:0xf
	v_fmac_f32_dpp v17, v17, v16 row_shr:2 row_mask:0xf bank_mask:0xf
	v_mul_f32_dpp v26, v26, v26 row_shr:2 row_mask:0xf bank_mask:0xf
	v_mul_f32_dpp v28, v28, v28 row_shr:2 row_mask:0xf bank_mask:0xf
	v_mul_f32_dpp v14, v14, v14 row_shr:2 row_mask:0xf bank_mask:0xf
	v_mul_f32_dpp v16, v16, v16 row_shr:2 row_mask:0xf bank_mask:0xf
	v_fmac_f32_dpp v27, v27, v26 row_shr:4 row_mask:0xf bank_mask:0xf
	v_fmac_f32_dpp v29, v29, v28 row_shr:4 row_mask:0xf bank_mask:0xf
	v_fmac_f32_dpp v15, v15, v14 row_shr:4 row_mask:0xf bank_mask:0xf
	v_fmac_f32_dpp v17, v17, v16 row_shr:4 row_mask:0xf bank_mask:0xf
	v_mul_f32_dpp v26, v26, v26 row_shr:4 row_mask:0xf bank_mask:0xf
	v_mul_f32_dpp v28, v28, v28 row_shr:4 row_mask:0xf bank_mask:0xf
	v_mul_f32_dpp v14, v14, v14 row_shr:4 row_mask:0xf bank_mask:0xf
	v_mul_f32_dpp v16, v16, v16 row_shr:4 row_mask:0xf bank_mask:0xf
	v_fmac_f32_dpp v27, v27, v26 row_shr:8 row_mask:0xf bank_mask:0xf
	v_fmac_f32_dpp v29, v29, v28 row_shr:8 row_mask:0xf bank_mask:0xf
	v_fmac_f32_dpp v15, v15, v14 row_shr:8 row_mask:0xf bank_mask:0xf
	v_fmac_f32_dpp v17, v17, v16 row_shr:8 row_mask:0xf bank_mask:0xf
	v_mul_f32_dpp v26, v26, v26 row_shr:8 row_mask:0xf bank_mask:0xf
	v_mul_f32_dpp v28, v28, v28 row_shr:8 row_mask:0xf bank_mask:0xf
	v_mul_f32_dpp v14, v14, v14 row_shr:8 row_mask:0xf bank_mask:0xf
	v_mul_f32_dpp v16, v16, v16 row_shr:8 row_mask:0xf bank_mask:0xf
	v_fmac_f32_dpp v27, v27, v26 row_bcast:15 row_mask:0xa bank_mask:0xf
	v_fmac_f32_dpp v29, v29, v28 row_bcast:15 row_mask:0xa bank_mask:0xf
	v_fmac_f32_dpp v15, v15, v14 row_bcast:15 row_mask:0xa bank_mask:0xf
	v_fmac_f32_dpp v17, v17, v16 row_bcast:15 row_mask:0xa bank_mask:0xf
	v_mul_f32_dpp v26, v26, v26 row_bcast:15 row_mask:0xa bank_mask:0xf
	v_mul_f32_dpp v28, v28, v28 row_bcast:15 row_mask:0xa bank_mask:0xf
	v_mul_f32_dpp v14, v14, v14 row_bcast:15 row_mask:0xa bank_mask:0xf
	v_mul_f32_dpp v16, v16, v16 row_bcast:15 row_mask:0xa bank_mask:0xf

; __device__ __forceinline__ unsigned cvt_pk_bf16(float lo, float hi) { unsigned r; asm volatile("v_cvt_pk_bf16_f32 %0, %1, %2" : "=v"(r) : "v"(lo), "v"(hi)); return r; }
; template <int PASS>
; __device__ __forceinline__ void lru_unit(const LruPtrs& args, LAS unsigned char* lds, int chunk, int bl, int g, int ck) {
;     ...
;     for (int q = 0; q < 8; ++q) { v4u st;
; #pragma unroll
;         for (int p = 0; p < 4; ++p) st[p] = pg8::cvt_pk_bf16(av[q][p], uv[q][p]);
;         stash[q * 64] = st; }
;     }
;     ...
;     if (PASS == 1 && n == 31) {
; #pragma unroll
;         for (int q = 0; q < 8; ++q)
; #pragma unroll
;             for (int p = 0; p < 4; ++p) { const int ci = 8 * q + 4 * hi + p; WAG[(w * 64 + ci) * 2] = av[q][p]; WAG[(w * 64 + ci) * 2 + 1] = uv[q][p]; }
	s_nop 0
	v_cvt_pk_bf16_f32 v30, v66, v67
	v_cvt_pk_bf16_f32 v31, v68, v69
	v_cvt_pk_bf16_f32 v32, v34, v35
	v_cvt_pk_bf16_f32 v33, v36, v37
	s_nop 0
	v_addc_co_u32_e32 v73, vcc, 0, v73, vcc
	global_store_dwordx4 v[72:73], v[30:33], off offset:-4096
	v_cmp_eq_u32_e32 vcc, 31, v87
	s_nop 0
	v_cvt_pk_bf16_f32 v30, v50, v51
	v_cvt_pk_bf16_f32 v31, v52, v53
	v_cvt_pk_bf16_f32 v32, v38, v39
	v_cvt_pk_bf16_f32 v33, v40, v41
	global_store_dwordx4 v[70:71], v[30:33], off offset:1024
	s_nop 1
	v_cvt_pk_bf16_f32 v30, v54, v55
	v_cvt_pk_bf16_f32 v31, v56, v57
	v_cvt_pk_bf16_f32 v32, v42, v43
	v_cvt_pk_bf16_f32 v33, v44, v45
	global_store_dwordx4 v[70:71], v[30:33], off offset:2048
	s_nop 1
	v_cvt_pk_bf16_f32 v30, v58, v59
	v_cvt_pk_bf16_f32 v31, v60, v61
	v_cvt_pk_bf16_f32 v32, v46, v47
	v_cvt_pk_bf16_f32 v33, v48, v49
	global_store_dwordx4 v[70:71], v[30:33], off offset:3072
	s_nop 1
	v_cvt_pk_bf16_f32 v30, v62, v63
	v_cvt_pk_bf16_f32 v31, v64, v65
	v_cvt_pk_bf16_f32 v32, v2, v3
	v_cvt_pk_bf16_f32 v33, v4, v5
	global_store_dwordx4 v[72:73], v[30:33], off
	s_nop 1
	v_cvt_pk_bf16_f32 v30, v18, v19
	v_cvt_pk_bf16_f32 v31, v20, v21
	v_cvt_pk_bf16_f32 v32, v6, v7
	v_cvt_pk_bf16_f32 v33, v8, v9
	global_store_dwordx4 v[72:73], v[30:33], off offset:1024
	s_nop 1
	v_cvt_pk_bf16_f32 v30, v22, v23
	v_cvt_pk_bf16_f32 v31, v24, v25
	v_cvt_pk_bf16_f32 v32, v10, v11
	v_cvt_pk_bf16_f32 v33, v12, v13
	global_store_dwordx4 v[72:73], v[30:33], off offset:2048
	s_nop 1
	v_cvt_pk_bf16_f32 v30, v26, v27
	v_cvt_pk_bf16_f32 v31, v28, v29
	v_cvt_pk_bf16_f32 v32, v14, v15
	v_cvt_pk_bf16_f32 v33, v16, v17
	global_store_dwordx4 v[72:73], v[30:33], off offset:3072
	s_and_saveexec_b64 s[4:5], vcc
	s_cbranch_execz .LBB0_447
	v_or_b32_e32 v0, s47, v88
	v_lshl_add_u32 v0, v0, 3, 0
	ds_write_b128 v0, v[66:69]
	ds_write_b128 v0, v[34:37] offset:16
	ds_write_b128 v0, v[50:53] offset:64
	ds_write_b128 v0, v[38:41] offset:80
	ds_write_b128 v0, v[54:57] offset:128
	ds_write_b128 v0, v[42:45] offset:144
	ds_write_b128 v0, v[58:61] offset:192
	ds_write_b128 v0, v[46:49] offset:208
	ds_write_b128 v0, v[62:65] offset:256
	ds_write_b128 v0, v[2:5] offset:272
	ds_write_b128 v0, v[18:21] offset:320
	ds_write_b128 v0, v[6:9] offset:336
	ds_write_b128 v0, v[22:25] offset:384
	ds_write_b128 v0, v[10:13] offset:400
	ds_write_b128 v0, v[26:29] offset:448
	ds_write_b128 v0, v[14:17] offset:464
